# T5 + route_mfma sub-key fragment loads issued 8 at a time with next-block prefetch (were serialised one per MFMA)
# speedup vs baseline: 1.0113x; 1.0022x over previous
; #define GAS __attribute__((address_space(1)))
; template <int MASK> __device__ __forceinline__ int f2key(float f, int payload) { int b = __float_as_int(f); b ^= (b >> 31) & 0x7fffffff; return (b & ~MASK) | payload; }
; __device__ __forceinline__ void route_mfma(const bf16_t* __restrict__ PQb, const bf16_t* __restrict__ SKb, int* __restrict__ IDX, float* __restrict__ G) {
;     ...
;     for (int tile = blockIdx.x; tile < T / 32; tile += NBLK) {
;         const int tok = tile * 32 + c;
;         int sv[2][16];
; #pragma unroll
;         for (int p = 0; p < 2; ++p) {
;             const GAS bf16_t* qp = (const GAS bf16_t*)PQb + (size_t)tok * D + h * 256 + p * 128 + 8 * hi;
;             const GAS bf16_t* kp = (const GAS bf16_t*)SKb + ((size_t)(h * 2 + p) * 128 + c) * 128 + 8 * hi;
;             bf16x8 qf[8];
; #pragma unroll
;             for (int s = 0; s < 8; ++s) qf[s] = *(const GAS bf16x8*)(qp + 16 * s);
;             int t0[16];
; #pragma unroll
;             for (int i = 0; i < 16; ++i) t0[i] = (int)0x80000000;
; #pragma unroll 1
;             for (int blk = 0; blk < 4; ++blk) {
;                 f32x16 acc;
; #pragma unroll
;                 for (int r = 0; r < 16; ++r) acc[r] = 0.f;
; #pragma unroll
;                 for (int s = 0; s < 8; ++s)
;                     acc = __builtin_amdgcn_mfma_f32_32x32x16_bf16(*(const GAS bf16x8*)(kp + (size_t)blk * 32 * 128 + 16 * s), qf[s], acc, 0, 0, 0);
;                 int nk[16];
;                 const int pay = (32 * blk) | (hi << 2);
; #pragma unroll
;                 for (int r = 0; r < 16; ++r) nk[r] = f2key<0x7f>(acc[r], pay | ((r & 3) + 8 * (r >> 2)));
;                 bitonic_sort16<false>(nk);
; #pragma unroll
;                 for (int i = 0; i < 16; ++i) t0[i] = imax(t0[i], nk[i]);
;                 bitonic_merge16<true>(t0);
;             }
.LBB0_514:
	v_lshl_or_b32 v62, s14, 5, v68
	v_ashrrev_i32_e32 v63, 31, v62
	v_lshlrev_b64 v[4:5], 12, v[62:63]
	v_lshl_add_u64 v[64:65], v[52:53], 0, v[4:5]
	global_load_dwordx4 v[20:23], v[64:65], off
	global_load_dwordx4 v[24:27], v[64:65], off offset:32
	global_load_dwordx4 v[28:31], v[64:65], off offset:64
	global_load_dwordx4 v[32:35], v[64:65], off offset:96
	global_load_dwordx4 v[36:39], v[64:65], off offset:128
	global_load_dwordx4 v[40:43], v[64:65], off offset:160
	global_load_dwordx4 v[44:47], v[64:65], off offset:192
	global_load_dwordx4 v[48:51], v[64:65], off offset:224
	v_bfrev_b32_e32 v1, 1
	s_mov_b32 s12, 0
	v_mov_b64_e32 v[66:67], v[58:59]
	v_bfrev_b32_e32 v2, 1
	v_bfrev_b32_e32 v89, 1
	v_bfrev_b32_e32 v90, 1
	v_bfrev_b32_e32 v91, 1
	v_bfrev_b32_e32 v92, 1
	v_bfrev_b32_e32 v93, 1
	v_bfrev_b32_e32 v94, 1
	v_bfrev_b32_e32 v95, 1
	v_bfrev_b32_e32 v96, 1
	v_bfrev_b32_e32 v97, 1
	v_bfrev_b32_e32 v98, 1
	v_bfrev_b32_e32 v99, 1
	v_bfrev_b32_e32 v100, 1
	v_bfrev_b32_e32 v101, 1
	v_bfrev_b32_e32 v102, 1
	s_mov_b64 s[16:17], 0x2000
	global_load_dwordx4 v[128:131], v[66:67], off offset:-224
	global_load_dwordx4 v[132:135], v[66:67], off offset:-192
	global_load_dwordx4 v[136:139], v[66:67], off offset:-160
	global_load_dwordx4 v[140:143], v[66:67], off offset:-128
	global_load_dwordx4 v[144:147], v[66:67], off offset:-96
	global_load_dwordx4 v[148:151], v[66:67], off offset:-64
	global_load_dwordx4 v[152:155], v[66:67], off offset:-32
	global_load_dwordx4 v[156:159], v[66:67], off
.LBB0_515:
	s_waitcnt vmcnt(7)
	v_mfma_f32_32x32x16_bf16 v[4:19], v[128:131], v[20:23], 0
	s_waitcnt vmcnt(6)
	v_mfma_f32_32x32x16_bf16 v[4:19], v[132:135], v[24:27], v[4:19]
	s_waitcnt vmcnt(5)
	v_mfma_f32_32x32x16_bf16 v[4:19], v[136:139], v[28:31], v[4:19]
	s_waitcnt vmcnt(4)
	v_mfma_f32_32x32x16_bf16 v[4:19], v[140:143], v[32:35], v[4:19]
	s_waitcnt vmcnt(3)
	v_mfma_f32_32x32x16_bf16 v[4:19], v[144:147], v[36:39], v[4:19]
	s_waitcnt vmcnt(2)
	v_mfma_f32_32x32x16_bf16 v[4:19], v[148:151], v[40:43], v[4:19]
	s_waitcnt vmcnt(1)
	v_mfma_f32_32x32x16_bf16 v[4:19], v[152:155], v[44:47], v[4:19]
	s_waitcnt vmcnt(0)
	v_mfma_f32_32x32x16_bf16 v[4:19], v[156:159], v[48:51], v[4:19]
	v_lshl_add_u64 v[66:67], v[66:67], 0, s[16:17]
	s_cmpk_lg_i32 s12, 0x60
	s_cbranch_scc0 .Lrt_skip_1
	global_load_dwordx4 v[128:131], v[66:67], off offset:-224
	global_load_dwordx4 v[132:135], v[66:67], off offset:-192
	global_load_dwordx4 v[136:139], v[66:67], off offset:-160
	global_load_dwordx4 v[140:143], v[66:67], off offset:-128
	global_load_dwordx4 v[144:147], v[66:67], off offset:-96
	global_load_dwordx4 v[148:151], v[66:67], off offset:-64
	global_load_dwordx4 v[152:155], v[66:67], off offset:-32
	global_load_dwordx4 v[156:159], v[66:67], off
.Lrt_skip_1:
	v_add_u32_e32 v104, s12, v70
	s_add_i32 s12, s12, 32
	s_cmpk_lg_i32 s12, 0x80
	s_nop 8
	v_ashrrev_i32_e32 v103, 31, v4
	v_and_b32_e32 v103, 0x7fffff80, v103
	v_and_b32_e32 v4, 0xffffff80, v4
	v_xad_u32 v4, v103, v4, v104
	v_ashrrev_i32_e32 v103, 31, v5
	v_and_b32_e32 v5, 0xffffff80, v5
	v_bitop3_b32 v5, v103, v5, s3 bitop3:0x6c
	v_ashrrev_i32_e32 v103, 31, v6
	v_and_b32_e32 v6, 0xffffff80, v6
	v_bitop3_b32 v6, v103, v6, s3 bitop3:0x6c
	v_ashrrev_i32_e32 v103, 31, v7
	v_and_b32_e32 v7, 0xffffff80, v7
	v_bitop3_b32 v7, v103, v7, s3 bitop3:0x6c
	v_ashrrev_i32_e32 v103, 31, v8
	v_and_b32_e32 v8, 0xffffff80, v8
	v_bitop3_b32 v8, v103, v8, s3 bitop3:0x6c
	v_ashrrev_i32_e32 v103, 31, v9
	v_and_b32_e32 v9, 0xffffff80, v9
	v_bitop3_b32 v9, v103, v9, s3 bitop3:0x6c
	v_ashrrev_i32_e32 v103, 31, v10
	v_and_b32_e32 v10, 0xffffff80, v10
	v_bitop3_b32 v10, v103, v10, s3 bitop3:0x6c
	v_ashrrev_i32_e32 v103, 31, v11
	v_and_b32_e32 v11, 0xffffff80, v11
	v_bitop3_b32 v11, v103, v11, s3 bitop3:0x6c
	v_ashrrev_i32_e32 v103, 31, v12
	v_and_b32_e32 v12, 0xffffff80, v12
	v_bitop3_b32 v12, v103, v12, s3 bitop3:0x6c
	v_ashrrev_i32_e32 v103, 31, v13
	v_and_b32_e32 v13, 0xffffff80, v13
	v_bitop3_b32 v13, v103, v13, s3 bitop3:0x6c
	v_ashrrev_i32_e32 v103, 31, v14
	v_and_b32_e32 v14, 0xffffff80, v14
	v_bitop3_b32 v14, v103, v14, s3 bitop3:0x6c
	v_ashrrev_i32_e32 v103, 31, v15
	v_and_b32_e32 v15, 0xffffff80, v15
	v_bitop3_b32 v15, v103, v15, s3 bitop3:0x6c
	v_ashrrev_i32_e32 v103, 31, v16
	v_and_b32_e32 v16, 0xffffff80, v16
	v_bitop3_b32 v16, v103, v16, s3 bitop3:0x6c
	v_ashrrev_i32_e32 v103, 31, v17
	v_and_b32_e32 v17, 0xffffff80, v17
	v_bitop3_b32 v17, v103, v17, s3 bitop3:0x6c
	v_ashrrev_i32_e32 v103, 31, v18
	v_and_b32_e32 v18, 0xffffff80, v18
	v_bitop3_b32 v18, v103, v18, s3 bitop3:0x6c
	v_ashrrev_i32_e32 v103, 31, v19
	v_and_b32_e32 v19, 0xffffff80, v19
	v_bitop3_b32 v19, v103, v19, s3 bitop3:0x6c
	v_add3_u32 v5, v104, v5, 1
	v_add3_u32 v6, v104, v6, 2
	v_add3_u32 v7, v104, v7, 3
	v_add3_u32 v8, v104, v8, 8
	v_add3_u32 v9, v104, v9, 9
	v_add3_u32 v10, v104, v10, 10
	v_add3_u32 v11, v104, v11, 11
	v_add3_u32 v12, v104, v12, 16
	v_add3_u32 v13, v104, v13, 17
	v_add3_u32 v14, v104, v14, 18
	v_add3_u32 v15, v104, v15, 19
	v_add3_u32 v16, v104, v16, 24
	v_add3_u32 v17, v104, v17, 25
	v_add3_u32 v18, v104, v18, 26
	v_add3_u32 v19, v104, v19, 27
	v_max_i32_e32 v103, v4, v5
	v_min_i32_e32 v4, v4, v5
	v_max_i32_e32 v5, v6, v7
	v_min_i32_e32 v6, v6, v7
	v_max_i32_e32 v7, v8, v9
	v_min_i32_e32 v8, v8, v9
	v_max_i32_e32 v9, v10, v11
	v_min_i32_e32 v10, v10, v11
	v_max_i32_e32 v11, v12, v13
	v_min_i32_e32 v12, v12, v13
	v_max_i32_e32 v13, v14, v15
	v_min_i32_e32 v14, v14, v15
	v_max_i32_e32 v15, v16, v17
	v_min_i32_e32 v16, v16, v17
	v_max_i32_e32 v17, v18, v19
	v_min_i32_e32 v18, v18, v19
	v_max_i32_e32 v19, v4, v5
	v_min_i32_e32 v4, v4, v5
; template <int MASK> __device__ __forceinline__ int f2key(float f, int payload) { int b = __float_as_int(f); b ^= (b >> 31) & 0x7fffffff; return (b & ~MASK) | payload; }
; template <bool DESC> __device__ __forceinline__ void bitonic_sort16(int (&k)[16]) {
; #pragma unroll
;     for (int size = 2; size <= 16; size <<= 1)
; #pragma unroll
;         for (int stride = size >> 1; stride > 0; stride >>= 1)
; #pragma unroll
;             for (int i = 0; i < 16; ++i) {
;                 const int j = i ^ stride;
;                 if (j > i) { const bool dd = (((i & size) == 0) == DESC);
;                              const int a = k[i], b = k[j], mx = imax(a, b), mn = imin(a, b); k[i] = dd ? mx : mn; k[j] = dd ? mn : mx; }
;             }
; }
; __device__ __forceinline__ void route_mfma(const bf16_t* __restrict__ PQb, const bf16_t* __restrict__ SKb, int* __restrict__ IDX, float* __restrict__ G) {
;     ...
;                 for (int r = 0; r < 16; ++r) nk[r] = f2key<0x7f>(acc[r], pay | ((r & 3) + 8 * (r >> 2)));
;                 bitonic_sort16<false>(nk);
; #pragma unroll
;                 for (int i = 0; i < 16; ++i) t0[i] = imax(t0[i], nk[i]);
;                 bitonic_merge16<true>(t0);
	v_max_i32_e32 v5, v103, v6
	v_min_i32_e32 v6, v103, v6
	v_max_i32_e32 v103, v8, v9
	v_min_i32_e32 v8, v8, v9
	v_max_i32_e32 v9, v7, v10
	v_min_i32_e32 v7, v7, v10
	v_max_i32_e32 v10, v12, v13
	v_min_i32_e32 v12, v12, v13
	v_max_i32_e32 v13, v11, v14
	v_min_i32_e32 v11, v11, v14
	v_max_i32_e32 v14, v16, v17
	v_min_i32_e32 v16, v16, v17
	v_max_i32_e32 v17, v15, v18
	v_min_i32_e32 v15, v15, v18
	v_max_i32_e32 v18, v4, v6
	v_min_i32_e32 v4, v4, v6
	v_max_i32_e32 v6, v19, v5
	v_min_i32_e32 v5, v19, v5
	v_max_i32_e32 v19, v103, v9
	v_min_i32_e32 v9, v103, v9
	v_max_i32_e32 v103, v8, v7
	v_min_i32_e32 v7, v8, v7
	v_max_i32_e32 v8, v12, v11
	v_min_i32_e32 v11, v12, v11
	v_max_i32_e32 v12, v10, v13
	v_min_i32_e32 v10, v10, v13
	v_max_i32_e32 v13, v14, v17
	v_min_i32_e32 v14, v14, v17
	v_max_i32_e32 v17, v16, v15
	v_min_i32_e32 v15, v16, v15
	v_max_i32_e32 v16, v4, v19
	v_min_i32_e32 v4, v4, v19
	v_max_i32_e32 v19, v18, v9
	v_min_i32_e32 v9, v18, v9
	v_max_i32_e32 v18, v5, v103
	v_min_i32_e32 v5, v5, v103
	v_max_i32_e32 v103, v6, v7
	v_min_i32_e32 v6, v6, v7
	v_max_i32_e32 v7, v11, v13
	v_min_i32_e32 v11, v11, v13
	v_max_i32_e32 v13, v8, v14
	v_min_i32_e32 v8, v8, v14
	v_max_i32_e32 v14, v10, v17
	v_min_i32_e32 v10, v10, v17
	v_max_i32_e32 v17, v12, v15
	v_min_i32_e32 v12, v12, v15
	v_max_i32_e32 v15, v4, v5
	v_min_i32_e32 v4, v4, v5
	v_max_i32_e32 v5, v9, v6
	v_min_i32_e32 v6, v9, v6
	v_max_i32_e32 v9, v16, v18
	v_min_i32_e32 v16, v16, v18
	v_max_i32_e32 v18, v19, v103
	v_min_i32_e32 v19, v19, v103
	v_max_i32_e32 v103, v7, v14
	v_min_i32_e32 v7, v7, v14
	v_max_i32_e32 v14, v13, v17
	v_min_i32_e32 v13, v13, v17
	v_max_i32_e32 v17, v11, v10
	v_min_i32_e32 v10, v11, v10
	v_max_i32_e32 v11, v8, v12
	v_min_i32_e32 v8, v8, v12
	v_max_i32_e32 v12, v4, v6
	v_min_i32_e32 v4, v4, v6
	v_max_i32_e32 v6, v15, v5
	v_min_i32_e32 v5, v15, v5
	v_max_i32_e32 v15, v16, v19
	v_min_i32_e32 v16, v16, v19
	v_max_i32_e32 v19, v9, v18
	v_min_i32_e32 v9, v9, v18
	v_max_i32_e32 v18, v103, v14
	v_min_i32_e32 v14, v103, v14
	v_max_i32_e32 v103, v7, v13
	v_min_i32_e32 v7, v7, v13
	v_max_i32_e32 v13, v17, v11
	v_min_i32_e32 v11, v17, v11
	v_max_i32_e32 v17, v10, v8
	v_min_i32_e32 v8, v10, v8
	v_max_i32_e32 v10, v4, v18
	v_min_i32_e32 v4, v4, v18
	v_max_i32_e32 v18, v12, v14
	v_min_i32_e32 v12, v12, v14
	v_max_i32_e32 v14, v5, v103
	v_min_i32_e32 v5, v5, v103
	v_max_i32_e32 v103, v6, v7
	v_min_i32_e32 v6, v6, v7
	v_max_i32_e32 v7, v16, v13
	v_min_i32_e32 v13, v16, v13
	v_max_i32_e32 v16, v15, v11
	v_min_i32_e32 v11, v15, v11
	v_max_i32_e32 v15, v9, v17
	v_min_i32_e32 v9, v9, v17
	v_max_i32_e32 v17, v19, v8
	v_min_i32_e32 v8, v19, v8
	v_max_i32_e32 v19, v4, v13
	v_min_i32_e32 v4, v4, v13
	v_max_i32_e32 v13, v12, v11
	v_min_i32_e32 v11, v12, v11
	v_max_i32_e32 v12, v5, v9
	v_min_i32_e32 v5, v5, v9
	v_max_i32_e32 v9, v6, v8
	v_min_i32_e32 v6, v6, v8
	v_max_i32_e32 v8, v10, v7
	v_min_i32_e32 v7, v10, v7
	v_max_i32_e32 v10, v18, v16
	v_min_i32_e32 v16, v18, v16
	v_max_i32_e32 v18, v14, v15
	v_min_i32_e32 v14, v14, v15
	v_max_i32_e32 v15, v103, v17
	v_min_i32_e32 v17, v103, v17
	v_max_i32_e32 v103, v4, v5
	v_min_i32_e32 v4, v4, v5
	v_max_i32_e32 v5, v11, v6
	v_min_i32_e32 v6, v11, v6
	v_max_i32_e32 v11, v19, v12
	v_min_i32_e32 v12, v19, v12
	v_max_i32_e32 v19, v13, v9
	v_min_i32_e32 v9, v13, v9
	v_max_i32_e32 v13, v7, v14
	v_min_i32_e32 v7, v7, v14
	v_max_i32_e32 v14, v16, v17
	v_min_i32_e32 v16, v16, v17
	v_max_i32_e32 v17, v8, v18
	v_min_i32_e32 v8, v8, v18
	v_max_i32_e32 v18, v10, v15
	v_min_i32_e32 v10, v10, v15
	v_min_i32_e32 v15, v4, v6
	v_min_i32_e32 v104, v103, v5
	v_min_i32_e32 v105, v12, v9
	v_min_i32_e32 v106, v11, v19
	v_min_i32_e32 v107, v7, v16
	v_min_i32_e32 v108, v13, v14
	v_min_i32_e32 v109, v8, v10
	v_min_i32_e32 v110, v17, v18
	v_max_i32_e32 v1, v1, v15
	v_max3_i32 v2, v2, v4, v6
	v_max_i32_e32 v4, v89, v104
	v_max3_i32 v5, v90, v103, v5
	v_max_i32_e32 v6, v91, v105
	v_max3_i32 v9, v92, v12, v9
	v_max_i32_e32 v12, v93, v106
	v_max3_i32 v11, v94, v11, v19
	v_max_i32_e32 v15, v95, v107
	v_max3_i32 v7, v96, v7, v16
	v_max_i32_e32 v16, v97, v108
	v_max3_i32 v13, v98, v13, v14
	v_max_i32_e32 v14, v99, v109
	v_max3_i32 v8, v100, v8, v10
	v_max_i32_e32 v10, v101, v110
	v_max3_i32 v17, v102, v17, v18
	v_max_i32_e32 v18, v1, v15
	v_min_i32_e32 v1, v1, v15
	v_max_i32_e32 v15, v2, v7
	v_min_i32_e32 v2, v2, v7
	v_max_i32_e32 v7, v4, v16
	v_min_i32_e32 v4, v4, v16
	v_max_i32_e32 v16, v5, v13
	v_min_i32_e32 v5, v5, v13
	v_max_i32_e32 v13, v6, v14
	v_min_i32_e32 v6, v6, v14
	v_max_i32_e32 v14, v9, v8
	v_min_i32_e32 v8, v9, v8
	v_max_i32_e32 v9, v12, v10
	v_min_i32_e32 v10, v12, v10
	v_max_i32_e32 v12, v11, v17
	v_min_i32_e32 v11, v11, v17
	v_max_i32_e32 v17, v18, v13
	v_min_i32_e32 v13, v18, v13
	v_max_i32_e32 v18, v15, v14
	v_min_i32_e32 v14, v15, v14
	v_max_i32_e32 v15, v7, v9
	v_min_i32_e32 v7, v7, v9
	v_max_i32_e32 v9, v16, v12
	v_min_i32_e32 v12, v16, v12
	v_max_i32_e32 v16, v1, v6
	v_min_i32_e32 v1, v1, v6
	v_max_i32_e32 v6, v2, v8
	v_min_i32_e32 v2, v2, v8
	v_max_i32_e32 v8, v4, v10
	v_min_i32_e32 v4, v4, v10
	v_max_i32_e32 v10, v5, v11
	v_min_i32_e32 v5, v5, v11
	v_max_i32_e32 v11, v17, v15
	v_min_i32_e32 v15, v17, v15
	v_max_i32_e32 v17, v18, v9
	v_min_i32_e32 v9, v18, v9
	v_max_i32_e32 v18, v13, v7
	v_min_i32_e32 v7, v13, v7
	v_max_i32_e32 v13, v14, v12
	v_min_i32_e32 v12, v14, v12
	v_max_i32_e32 v14, v16, v8
	v_min_i32_e32 v8, v16, v8
	v_max_i32_e32 v16, v6, v10
	v_min_i32_e32 v6, v6, v10
	v_max_i32_e32 v10, v1, v4
	v_min_i32_e32 v4, v1, v4
	v_max_i32_e32 v19, v2, v5
	v_min_i32_e32 v5, v2, v5
	v_max_i32_e32 v1, v11, v17
	v_min_i32_e32 v2, v11, v17
	v_max_i32_e32 v89, v15, v9
	v_min_i32_e32 v90, v15, v9
	v_max_i32_e32 v91, v18, v13
	v_min_i32_e32 v92, v18, v13
	v_max_i32_e32 v93, v7, v12
	v_min_i32_e32 v94, v7, v12
	v_max_i32_e32 v95, v14, v16
	v_min_i32_e32 v96, v14, v16
	v_max_i32_e32 v97, v8, v6
	v_min_i32_e32 v98, v8, v6
	v_max_i32_e32 v99, v10, v19
	v_min_i32_e32 v100, v10, v19
	v_max_i32_e32 v101, v4, v5
	v_min_i32_e32 v102, v4, v5
	s_cbranch_scc1 .LBB0_515
; #define GAS __attribute__((address_space(1)))
; __device__ __forceinline__ void partner_merge16(int (&k)[16], int hi) {
;     int pr[16];
; #pragma unroll
;     for (int i = 0; i < 16; ++i) { auto rr = __builtin_amdgcn_permlane32_swap((unsigned)k[i], (unsigned)k[i], false, false); pr[i] = hi ? (int)rr[0] : (int)rr[1]; }
; #pragma unroll
;     for (int i = 0; i < 16; ++i) k[i] = imax(k[i], pr[15 - i]);
;     bitonic_merge16<true>(k);
; __device__ __forceinline__ void route_mfma(const bf16_t* __restrict__ PQb, const bf16_t* __restrict__ SKb, int* __restrict__ IDX, float* __restrict__ G) {
;     ...
;         for (int p = 0; p < 2; ++p) {
;             const GAS bf16_t* qp = (const GAS bf16_t*)PQb + (size_t)tok * D + h * 256 + p * 128 + 8 * hi;
;             const GAS bf16_t* kp = (const GAS bf16_t*)SKb + ((size_t)(h * 2 + p) * 128 + c) * 128 + 8 * hi;
;             bf16x8 qf[8];
; #pragma unroll
;             for (int s = 0; s < 8; ++s) qf[s] = *(const GAS bf16x8*)(qp + 16 * s);
;             int t0[16];
; #pragma unroll
;             for (int i = 0; i < 16; ++i) t0[i] = (int)0x80000000;
; #pragma unroll 1
;             for (int blk = 0; blk < 4; ++blk) {
;                 f32x16 acc;
; #pragma unroll
;                 for (int r = 0; r < 16; ++r) acc[r] = 0.f;
; #pragma unroll
;                 for (int s = 0; s < 8; ++s)
;                     acc = __builtin_amdgcn_mfma_f32_32x32x16_bf16(*(const GAS bf16x8*)(kp + (size_t)blk * 32 * 128 + 16 * s), qf[s], acc, 0, 0, 0);
;                 int nk[16];
;                 const int pay = (32 * blk) | (hi << 2);
; #pragma unroll
;                 for (int r = 0; r < 16; ++r) nk[r] = f2key<0x7f>(acc[r], pay | ((r & 3) + 8 * (r >> 2)));
;                 bitonic_sort16<false>(nk);
; #pragma unroll
;                 for (int i = 0; i < 16; ++i) t0[i] = imax(t0[i], nk[i]);
;                 bitonic_merge16<true>(t0);
;             }
;             partner_merge16(t0, hi);
; #pragma unroll
;             for (int i = 0; i < 16; ++i) sv[p][i] = t0[i];
; #pragma unroll
;             for (int q4 = 0; q4 < 4; ++q4)
;                 *(unsigned*)(myslot + p * 16 + q4 * 4) = (unsigned)(t0[4 * q4] & 0x7f) | ((unsigned)(t0[4 * q4 + 1] & 0x7f) << 8) | ((unsigned)(t0[4 * q4 + 2] & 0x7f) << 16) | ((unsigned)(t0[4 * q4 + 3] & 0x7f) << 24);
	v_mov_b32_e32 v4, v1
	v_mov_b32_e32 v5, v1
	s_nop 1
	v_permlane32_swap_b32_e32 v4, v5
	v_cndmask_b32_e64 v4, v4, v5, s[42:43]
	v_mov_b32_e32 v5, v2
	v_mov_b32_e32 v6, v2
	s_nop 1
	v_permlane32_swap_b32_e32 v5, v6
	v_cndmask_b32_e64 v5, v5, v6, s[42:43]
	v_mov_b32_e32 v6, v89
	v_mov_b32_e32 v7, v89
	s_nop 1
	v_permlane32_swap_b32_e32 v6, v7
	v_cndmask_b32_e64 v6, v6, v7, s[42:43]
	v_mov_b32_e32 v7, v90
	v_mov_b32_e32 v8, v90
	s_nop 1
	v_permlane32_swap_b32_e32 v7, v8
	v_cndmask_b32_e64 v7, v7, v8, s[42:43]
	v_mov_b32_e32 v8, v91
	v_mov_b32_e32 v9, v91
	s_nop 1
	v_permlane32_swap_b32_e32 v8, v9
	v_cndmask_b32_e64 v8, v8, v9, s[42:43]
	v_mov_b32_e32 v9, v92
	v_mov_b32_e32 v10, v92
	s_nop 1
	v_permlane32_swap_b32_e32 v9, v10
	v_cndmask_b32_e64 v9, v9, v10, s[42:43]
	v_mov_b32_e32 v10, v93
	v_mov_b32_e32 v11, v93
	s_nop 1
	v_permlane32_swap_b32_e32 v10, v11
	v_cndmask_b32_e64 v10, v10, v11, s[42:43]
	v_mov_b32_e32 v11, v94
	v_mov_b32_e32 v12, v94
	s_nop 1
	v_permlane32_swap_b32_e32 v11, v12
	v_cndmask_b32_e64 v11, v11, v12, s[42:43]
	v_mov_b32_e32 v12, v95
	v_mov_b32_e32 v13, v95
	s_nop 1
	v_permlane32_swap_b32_e32 v12, v13
	v_cndmask_b32_e64 v12, v12, v13, s[42:43]
	v_mov_b32_e32 v13, v96
	v_mov_b32_e32 v14, v96
	s_nop 1
	v_permlane32_swap_b32_e32 v13, v14
	v_cndmask_b32_e64 v13, v13, v14, s[42:43]
	v_mov_b32_e32 v14, v97
	v_mov_b32_e32 v15, v97
	s_nop 1
	v_permlane32_swap_b32_e32 v14, v15
	v_cndmask_b32_e64 v14, v14, v15, s[42:43]
	v_mov_b32_e32 v15, v98
	v_mov_b32_e32 v16, v98
	s_nop 1
	v_permlane32_swap_b32_e32 v15, v16
	v_cndmask_b32_e64 v15, v15, v16, s[42:43]
	v_mov_b32_e32 v16, v99
	v_mov_b32_e32 v17, v99
	s_nop 1
	v_permlane32_swap_b32_e32 v16, v17
	v_cndmask_b32_e64 v16, v16, v17, s[42:43]
	v_mov_b32_e32 v17, v100
	v_mov_b32_e32 v18, v100
	s_nop 1
	v_permlane32_swap_b32_e32 v17, v18
	v_cndmask_b32_e64 v17, v17, v18, s[42:43]
	v_mov_b32_e32 v18, v101
	v_mov_b32_e32 v19, v101
	s_nop 1
	v_permlane32_swap_b32_e32 v18, v19
	v_cndmask_b32_e64 v18, v18, v19, s[42:43]
	v_mov_b32_e32 v19, v102
	v_mov_b32_e32 v20, v102
	s_nop 1
	v_permlane32_swap_b32_e32 v19, v20
	v_cndmask_b32_e64 v19, v19, v20, s[42:43]
	v_max_i32_e32 v1, v1, v19
	v_max_i32_e32 v2, v2, v18
	v_max_i32_e32 v17, v89, v17
	v_max_i32_e32 v16, v90, v16
	v_max_i32_e32 v15, v91, v15
	v_max_i32_e32 v14, v92, v14
	v_max_i32_e32 v13, v93, v13
	v_max_i32_e32 v12, v94, v12
	v_max_i32_e32 v11, v95, v11
	v_max_i32_e32 v10, v96, v10
	v_max_i32_e32 v9, v97, v9
	v_max_i32_e32 v8, v98, v8
	v_max_i32_e32 v7, v99, v7
	v_max_i32_e32 v6, v100, v6
	v_max_i32_e32 v5, v101, v5
	v_max_i32_e32 v4, v102, v4
	v_max_i32_e32 v18, v1, v11
	v_min_i32_e32 v1, v1, v11
	v_max_i32_e32 v11, v2, v10
	v_min_i32_e32 v2, v2, v10
	v_max_i32_e32 v10, v17, v9
	v_min_i32_e32 v9, v17, v9
	v_max_i32_e32 v17, v16, v8
	v_min_i32_e32 v8, v16, v8
	v_max_i32_e32 v16, v15, v7
	v_min_i32_e32 v7, v15, v7
	v_max_i32_e32 v15, v14, v6
	v_min_i32_e32 v6, v14, v6
	v_max_i32_e32 v14, v13, v5
	v_min_i32_e32 v5, v13, v5
	v_max_i32_e32 v13, v12, v4
	v_min_i32_e32 v4, v12, v4
	v_max_i32_e32 v12, v18, v16
	v_min_i32_e32 v16, v18, v16
	v_max_i32_e32 v18, v11, v15
	v_min_i32_e32 v11, v11, v15
	v_max_i32_e32 v15, v10, v14
	v_min_i32_e32 v10, v10, v14
	v_max_i32_e32 v14, v17, v13
	v_min_i32_e32 v13, v17, v13
	v_max_i32_e32 v17, v1, v7
	v_min_i32_e32 v1, v1, v7
	v_max_i32_e32 v7, v2, v6
	v_min_i32_e32 v2, v2, v6
	v_max_i32_e32 v6, v9, v5
	v_min_i32_e32 v5, v9, v5
	v_max_i32_e32 v9, v8, v4
	v_min_i32_e32 v4, v8, v4
	v_max_i32_e32 v8, v12, v15
	v_min_i32_e32 v12, v12, v15
	v_max_i32_e32 v15, v18, v14
	v_min_i32_e32 v14, v18, v14
	v_max_i32_e32 v18, v16, v10
	v_min_i32_e32 v10, v16, v10
	v_max_i32_e32 v16, v11, v13
	v_min_i32_e32 v11, v11, v13
	v_max_i32_e32 v13, v17, v6
	v_min_i32_e32 v6, v17, v6
	v_max_i32_e32 v17, v7, v9
	v_min_i32_e32 v7, v7, v9
	v_max_i32_e32 v9, v1, v5
	v_min_i32_e32 v5, v1, v5
	v_max_i32_e32 v19, v2, v4
	v_min_i32_e32 v2, v2, v4
	v_max_i32_e32 v1, v8, v15
	v_min_i32_e32 v92, v8, v15
	v_max_i32_e32 v91, v12, v14
	v_min_i32_e32 v90, v12, v14
	v_max_i32_e32 v96, v5, v2
	v_min_i32_e32 v100, v5, v2
	v_and_b32_e32 v2, 0x7f, v1
	v_lshlrev_b32_e32 v4, 8, v92
	s_movk_i32 s12, 0x7f00
	v_and_or_b32 v2, v4, s12, v2
	v_lshlrev_b32_e32 v4, 16, v91
	v_lshlrev_b32_e32 v5, 24, v90
	v_max_i32_e32 v89, v18, v16
	v_min_i32_e32 v67, v18, v16
	v_and_b32_e32 v4, 0x7f0000, v4
	v_and_b32_e32 v5, 0x7f000000, v5
	v_max_i32_e32 v66, v10, v11
	v_min_i32_e32 v101, v10, v11
	v_or3_b32 v4, v2, v4, v5
	v_and_b32_e32 v2, 0x7f, v89
	v_lshlrev_b32_e32 v5, 8, v67
	v_max_i32_e32 v94, v6, v7
	v_min_i32_e32 v98, v6, v7
	v_and_or_b32 v2, v5, s12, v2
	v_lshlrev_b32_e32 v5, 16, v66
	v_lshlrev_b32_e32 v6, 24, v101
	v_max_i32_e32 v93, v13, v17
	v_min_i32_e32 v97, v13, v17
	v_and_b32_e32 v5, 0x7f0000, v5
	v_and_b32_e32 v6, 0x7f000000, v6
	v_or3_b32 v5, v2, v5, v6
	v_and_b32_e32 v2, 0x7f, v93
	v_lshlrev_b32_e32 v6, 8, v97
	v_and_or_b32 v2, v6, s12, v2
	v_lshlrev_b32_e32 v6, 16, v94
	v_lshlrev_b32_e32 v7, 24, v98
	v_max_i32_e32 v95, v9, v19
	v_min_i32_e32 v99, v9, v19
	v_and_b32_e32 v6, 0x7f0000, v6
	v_and_b32_e32 v7, 0x7f000000, v7
	v_or3_b32 v6, v2, v6, v7
	v_and_b32_e32 v2, 0x7f, v95
	v_lshlrev_b32_e32 v7, 8, v99
	v_and_or_b32 v2, v7, s12, v2
	v_lshlrev_b32_e32 v7, 16, v96
	v_lshlrev_b32_e32 v8, 24, v100
	v_and_b32_e32 v7, 0x7f0000, v7
	v_and_b32_e32 v8, 0x7f000000, v8
	v_or3_b32 v7, v2, v7, v8
	ds_write_b128 v69, v[4:7]
	global_load_dwordx4 v[20:23], v[64:65], off offset:256
	global_load_dwordx4 v[24:27], v[64:65], off offset:288
	global_load_dwordx4 v[28:31], v[64:65], off offset:320
	global_load_dwordx4 v[32:35], v[64:65], off offset:352
	global_load_dwordx4 v[36:39], v[64:65], off offset:384
	global_load_dwordx4 v[40:43], v[64:65], off offset:416
	global_load_dwordx4 v[44:47], v[64:65], off offset:448
	global_load_dwordx4 v[48:51], v[64:65], off offset:480
	v_bfrev_b32_e32 v2, 1
	s_mov_b32 s12, 0
	v_mov_b64_e32 v[64:65], v[60:61]
	v_bfrev_b32_e32 v102, 1
	v_bfrev_b32_e32 v103, 1
	v_bfrev_b32_e32 v104, 1
	v_bfrev_b32_e32 v105, 1
	v_bfrev_b32_e32 v106, 1
	v_bfrev_b32_e32 v107, 1
	v_bfrev_b32_e32 v108, 1
	v_bfrev_b32_e32 v109, 1
	v_bfrev_b32_e32 v110, 1
	v_bfrev_b32_e32 v111, 1
	v_bfrev_b32_e32 v112, 1
	v_bfrev_b32_e32 v113, 1
	v_bfrev_b32_e32 v114, 1
	v_bfrev_b32_e32 v115, 1
	v_bfrev_b32_e32 v116, 1
	global_load_dwordx4 v[128:131], v[64:65], off offset:-128
	global_load_dwordx4 v[132:135], v[64:65], off offset:-96
	global_load_dwordx4 v[136:139], v[64:65], off offset:-64
	global_load_dwordx4 v[140:143], v[64:65], off offset:-32
	global_load_dwordx4 v[144:147], v[64:65], off
	global_load_dwordx4 v[148:151], v[64:65], off offset:32
	global_load_dwordx4 v[152:155], v[64:65], off offset:64
	global_load_dwordx4 v[156:159], v[64:65], off offset:96
; #define GAS __attribute__((address_space(1)))
; template <int MASK> __device__ __forceinline__ int f2key(float f, int payload) { int b = __float_as_int(f); b ^= (b >> 31) & 0x7fffffff; return (b & ~MASK) | payload; }
; __device__ __forceinline__ void route_mfma(const bf16_t* __restrict__ PQb, const bf16_t* __restrict__ SKb, int* __restrict__ IDX, float* __restrict__ G) {
;     ...
; #pragma unroll 1
;             for (int blk = 0; blk < 4; ++blk) {
;                 f32x16 acc;
; #pragma unroll
;                 for (int r = 0; r < 16; ++r) acc[r] = 0.f;
; #pragma unroll
;                 for (int s = 0; s < 8; ++s)
;                     acc = __builtin_amdgcn_mfma_f32_32x32x16_bf16(*(const GAS bf16x8*)(kp + (size_t)blk * 32 * 128 + 16 * s), qf[s], acc, 0, 0, 0);
;                 int nk[16];
;                 const int pay = (32 * blk) | (hi << 2);
; #pragma unroll
;                 for (int r = 0; r < 16; ++r) nk[r] = f2key<0x7f>(acc[r], pay | ((r & 3) + 8 * (r >> 2)));
;                 bitonic_sort16<false>(nk);
; #pragma unroll
;                 for (int i = 0; i < 16; ++i) t0[i] = imax(t0[i], nk[i]);
;                 bitonic_merge16<true>(t0);
;             }
.LBB0_517:
	s_waitcnt vmcnt(7)
	v_mfma_f32_32x32x16_bf16 v[4:19], v[128:131], v[20:23], 0
	s_waitcnt vmcnt(6)
	v_mfma_f32_32x32x16_bf16 v[4:19], v[132:135], v[24:27], v[4:19]
	s_waitcnt vmcnt(5)
	v_mfma_f32_32x32x16_bf16 v[4:19], v[136:139], v[28:31], v[4:19]
	s_waitcnt vmcnt(4)
	v_mfma_f32_32x32x16_bf16 v[4:19], v[140:143], v[32:35], v[4:19]
	s_waitcnt vmcnt(3)
	v_mfma_f32_32x32x16_bf16 v[4:19], v[144:147], v[36:39], v[4:19]
	s_waitcnt vmcnt(2)
	v_mfma_f32_32x32x16_bf16 v[4:19], v[148:151], v[40:43], v[4:19]
	s_waitcnt vmcnt(1)
	v_mfma_f32_32x32x16_bf16 v[4:19], v[152:155], v[44:47], v[4:19]
	s_waitcnt vmcnt(0)
	v_mfma_f32_32x32x16_bf16 v[4:19], v[156:159], v[48:51], v[4:19]
	v_lshl_add_u64 v[64:65], v[64:65], 0, s[16:17]
	s_cmpk_lg_i32 s12, 0x60
	s_cbranch_scc0 .Lrt_skip_2
	global_load_dwordx4 v[128:131], v[64:65], off offset:-128
	global_load_dwordx4 v[132:135], v[64:65], off offset:-96
	global_load_dwordx4 v[136:139], v[64:65], off offset:-64
	global_load_dwordx4 v[140:143], v[64:65], off offset:-32
	global_load_dwordx4 v[144:147], v[64:65], off
	global_load_dwordx4 v[148:151], v[64:65], off offset:32
	global_load_dwordx4 v[152:155], v[64:65], off offset:64
	global_load_dwordx4 v[156:159], v[64:65], off offset:96
.Lrt_skip_2:
	v_add_u32_e32 v118, s12, v70
	s_add_i32 s12, s12, 32
	s_cmpk_lg_i32 s12, 0x80
	s_nop 8
	v_ashrrev_i32_e32 v117, 31, v4
	v_and_b32_e32 v117, 0x7fffff80, v117
	v_and_b32_e32 v4, 0xffffff80, v4
	v_xad_u32 v4, v117, v4, v118
	v_ashrrev_i32_e32 v117, 31, v5
	v_and_b32_e32 v5, 0xffffff80, v5
	v_bitop3_b32 v5, v117, v5, s3 bitop3:0x6c
	v_ashrrev_i32_e32 v117, 31, v6
	v_and_b32_e32 v6, 0xffffff80, v6
	v_bitop3_b32 v6, v117, v6, s3 bitop3:0x6c
	v_ashrrev_i32_e32 v117, 31, v7
	v_and_b32_e32 v7, 0xffffff80, v7
	v_bitop3_b32 v7, v117, v7, s3 bitop3:0x6c
	v_ashrrev_i32_e32 v117, 31, v8
	v_and_b32_e32 v8, 0xffffff80, v8
	v_bitop3_b32 v8, v117, v8, s3 bitop3:0x6c
	v_ashrrev_i32_e32 v117, 31, v9
	v_and_b32_e32 v9, 0xffffff80, v9
	v_bitop3_b32 v9, v117, v9, s3 bitop3:0x6c
	v_ashrrev_i32_e32 v117, 31, v10
	v_and_b32_e32 v10, 0xffffff80, v10
	v_bitop3_b32 v10, v117, v10, s3 bitop3:0x6c
	v_ashrrev_i32_e32 v117, 31, v11
	v_and_b32_e32 v11, 0xffffff80, v11
	v_bitop3_b32 v11, v117, v11, s3 bitop3:0x6c
	v_ashrrev_i32_e32 v117, 31, v12
	v_and_b32_e32 v12, 0xffffff80, v12
	v_bitop3_b32 v12, v117, v12, s3 bitop3:0x6c
	v_ashrrev_i32_e32 v117, 31, v13
	v_and_b32_e32 v13, 0xffffff80, v13
	v_bitop3_b32 v13, v117, v13, s3 bitop3:0x6c
	v_ashrrev_i32_e32 v117, 31, v14
	v_and_b32_e32 v14, 0xffffff80, v14
	v_bitop3_b32 v14, v117, v14, s3 bitop3:0x6c
	v_ashrrev_i32_e32 v117, 31, v15
	v_and_b32_e32 v15, 0xffffff80, v15
	v_bitop3_b32 v15, v117, v15, s3 bitop3:0x6c
	v_ashrrev_i32_e32 v117, 31, v16
	v_and_b32_e32 v16, 0xffffff80, v16
	v_bitop3_b32 v16, v117, v16, s3 bitop3:0x6c
	v_ashrrev_i32_e32 v117, 31, v17
	v_and_b32_e32 v17, 0xffffff80, v17
	v_bitop3_b32 v17, v117, v17, s3 bitop3:0x6c
	v_ashrrev_i32_e32 v117, 31, v18
	v_and_b32_e32 v18, 0xffffff80, v18
	v_bitop3_b32 v18, v117, v18, s3 bitop3:0x6c
	v_ashrrev_i32_e32 v117, 31, v19
	v_and_b32_e32 v19, 0xffffff80, v19
	v_bitop3_b32 v19, v117, v19, s3 bitop3:0x6c
	v_add3_u32 v5, v118, v5, 1
	v_add3_u32 v6, v118, v6, 2
	v_add3_u32 v7, v118, v7, 3
	v_add3_u32 v8, v118, v8, 8
	v_add3_u32 v9, v118, v9, 9
	v_add3_u32 v10, v118, v10, 10
	v_add3_u32 v11, v118, v11, 11
	v_add3_u32 v12, v118, v12, 16
	v_add3_u32 v13, v118, v13, 17
	v_add3_u32 v14, v118, v14, 18
	v_add3_u32 v15, v118, v15, 19
	v_add3_u32 v16, v118, v16, 24
	v_add3_u32 v17, v118, v17, 25
	v_add3_u32 v18, v118, v18, 26
	v_add3_u32 v19, v118, v19, 27
	v_max_i32_e32 v117, v4, v5
	v_min_i32_e32 v4, v4, v5
	v_max_i32_e32 v5, v6, v7
	v_min_i32_e32 v6, v6, v7
	v_max_i32_e32 v7, v8, v9
	v_min_i32_e32 v8, v8, v9
	v_max_i32_e32 v9, v10, v11
	v_min_i32_e32 v10, v10, v11
	v_max_i32_e32 v11, v12, v13
	v_min_i32_e32 v12, v12, v13
	v_max_i32_e32 v13, v14, v15
	v_min_i32_e32 v14, v14, v15
	v_max_i32_e32 v15, v16, v17
	v_min_i32_e32 v16, v16, v17
	v_max_i32_e32 v17, v18, v19
	v_min_i32_e32 v18, v18, v19
	v_max_i32_e32 v19, v4, v5
	v_min_i32_e32 v4, v4, v5
	v_max_i32_e32 v5, v117, v6
	v_min_i32_e32 v6, v117, v6
	v_max_i32_e32 v117, v8, v9
	v_min_i32_e32 v8, v8, v9
	v_max_i32_e32 v9, v7, v10
	v_min_i32_e32 v7, v7, v10
	v_max_i32_e32 v10, v12, v13
	v_min_i32_e32 v12, v12, v13
	v_max_i32_e32 v13, v11, v14
	v_min_i32_e32 v11, v11, v14
	v_max_i32_e32 v14, v16, v17
	v_min_i32_e32 v16, v16, v17
	v_max_i32_e32 v17, v15, v18
	v_min_i32_e32 v15, v15, v18
	v_max_i32_e32 v18, v4, v6
	v_min_i32_e32 v4, v4, v6
	v_max_i32_e32 v6, v19, v5
	v_min_i32_e32 v5, v19, v5
	v_max_i32_e32 v19, v117, v9
	v_min_i32_e32 v9, v117, v9
	v_max_i32_e32 v117, v8, v7
	v_min_i32_e32 v7, v8, v7
	v_max_i32_e32 v8, v12, v11
	v_min_i32_e32 v11, v12, v11
	v_max_i32_e32 v12, v10, v13
	v_min_i32_e32 v10, v10, v13
	v_max_i32_e32 v13, v14, v17
	v_min_i32_e32 v14, v14, v17
	v_max_i32_e32 v17, v16, v15
	v_min_i32_e32 v15, v16, v15
	v_max_i32_e32 v16, v4, v19
	v_min_i32_e32 v4, v4, v19
	v_max_i32_e32 v19, v18, v9
	v_min_i32_e32 v9, v18, v9
	v_max_i32_e32 v18, v5, v117
	v_min_i32_e32 v5, v5, v117
	v_max_i32_e32 v117, v6, v7
	v_min_i32_e32 v6, v6, v7
	v_max_i32_e32 v7, v11, v13
	v_min_i32_e32 v11, v11, v13
	v_max_i32_e32 v13, v8, v14
	v_min_i32_e32 v8, v8, v14
	v_max_i32_e32 v14, v10, v17
	v_min_i32_e32 v10, v10, v17
	v_max_i32_e32 v17, v12, v15
	v_min_i32_e32 v12, v12, v15
	v_max_i32_e32 v15, v4, v5
	v_min_i32_e32 v4, v4, v5
	v_max_i32_e32 v5, v9, v6
	v_min_i32_e32 v6, v9, v6
	v_max_i32_e32 v9, v16, v18
	v_min_i32_e32 v16, v16, v18
	v_max_i32_e32 v18, v19, v117
	v_min_i32_e32 v19, v19, v117
	v_max_i32_e32 v117, v7, v14
; template <int MASK> __device__ __forceinline__ int f2key(float f, int payload) { int b = __float_as_int(f); b ^= (b >> 31) & 0x7fffffff; return (b & ~MASK) | payload; }
; template <bool DESC> __device__ __forceinline__ void bitonic_sort16(int (&k)[16]) {
; #pragma unroll
;     for (int size = 2; size <= 16; size <<= 1)
; #pragma unroll
;         for (int stride = size >> 1; stride > 0; stride >>= 1)
; #pragma unroll
;             for (int i = 0; i < 16; ++i) {
;                 const int j = i ^ stride;
;                 if (j > i) { const bool dd = (((i & size) == 0) == DESC);
;                              const int a = k[i], b = k[j], mx = imax(a, b), mn = imin(a, b); k[i] = dd ? mx : mn; k[j] = dd ? mn : mx; }
;             }
; }
; template <bool DESC> __device__ __forceinline__ void bitonic_merge16(int (&k)[16]) {
; #pragma unroll
;     for (int stride = 8; stride > 0; stride >>= 1)
; #pragma unroll
;         for (int i = 0; i < 16; ++i) {
;             const int j = i ^ stride;
;             if (j > i) { const int a = k[i], b = k[j], mx = imax(a, b), mn = imin(a, b); k[i] = DESC ? mx : mn; k[j] = DESC ? mn : mx; }
;         }
; }
; __device__ __forceinline__ void route_mfma(const bf16_t* __restrict__ PQb, const bf16_t* __restrict__ SKb, int* __restrict__ IDX, float* __restrict__ G) {
;     ...
;                 for (int r = 0; r < 16; ++r) nk[r] = f2key<0x7f>(acc[r], pay | ((r & 3) + 8 * (r >> 2)));
;                 bitonic_sort16<false>(nk);
; #pragma unroll
;                 for (int i = 0; i < 16; ++i) t0[i] = imax(t0[i], nk[i]);
;                 bitonic_merge16<true>(t0);
	v_min_i32_e32 v7, v7, v14
	v_max_i32_e32 v14, v13, v17
	v_min_i32_e32 v13, v13, v17
	v_max_i32_e32 v17, v11, v10
	v_min_i32_e32 v10, v11, v10
	v_max_i32_e32 v11, v8, v12
	v_min_i32_e32 v8, v8, v12
	v_max_i32_e32 v12, v4, v6
	v_min_i32_e32 v4, v4, v6
	v_max_i32_e32 v6, v15, v5
	v_min_i32_e32 v5, v15, v5
	v_max_i32_e32 v15, v16, v19
	v_min_i32_e32 v16, v16, v19
	v_max_i32_e32 v19, v9, v18
	v_min_i32_e32 v9, v9, v18
	v_max_i32_e32 v18, v117, v14
	v_min_i32_e32 v14, v117, v14
	v_max_i32_e32 v117, v7, v13
	v_min_i32_e32 v7, v7, v13
	v_max_i32_e32 v13, v17, v11
	v_min_i32_e32 v11, v17, v11
	v_max_i32_e32 v17, v10, v8
	v_min_i32_e32 v8, v10, v8
	v_max_i32_e32 v10, v4, v18
	v_min_i32_e32 v4, v4, v18
	v_max_i32_e32 v18, v12, v14
	v_min_i32_e32 v12, v12, v14
	v_max_i32_e32 v14, v5, v117
	v_min_i32_e32 v5, v5, v117
	v_max_i32_e32 v117, v6, v7
	v_min_i32_e32 v6, v6, v7
	v_max_i32_e32 v7, v16, v13
	v_min_i32_e32 v13, v16, v13
	v_max_i32_e32 v16, v15, v11
	v_min_i32_e32 v11, v15, v11
	v_max_i32_e32 v15, v9, v17
	v_min_i32_e32 v9, v9, v17
	v_max_i32_e32 v17, v19, v8
	v_min_i32_e32 v8, v19, v8
	v_max_i32_e32 v19, v4, v13
	v_min_i32_e32 v4, v4, v13
	v_max_i32_e32 v13, v12, v11
	v_min_i32_e32 v11, v12, v11
	v_max_i32_e32 v12, v5, v9
	v_min_i32_e32 v5, v5, v9
	v_max_i32_e32 v9, v6, v8
	v_min_i32_e32 v6, v6, v8
	v_max_i32_e32 v8, v10, v7
	v_min_i32_e32 v7, v10, v7
	v_max_i32_e32 v10, v18, v16
	v_min_i32_e32 v16, v18, v16
	v_max_i32_e32 v18, v14, v15
	v_min_i32_e32 v14, v14, v15
	v_max_i32_e32 v15, v117, v17
	v_min_i32_e32 v17, v117, v17
	v_max_i32_e32 v117, v4, v5
	v_min_i32_e32 v4, v4, v5
	v_max_i32_e32 v5, v11, v6
	v_min_i32_e32 v6, v11, v6
	v_max_i32_e32 v11, v19, v12
	v_min_i32_e32 v12, v19, v12
	v_max_i32_e32 v19, v13, v9
	v_min_i32_e32 v9, v13, v9
	v_max_i32_e32 v13, v7, v14
	v_min_i32_e32 v7, v7, v14
	v_max_i32_e32 v14, v16, v17
	v_min_i32_e32 v16, v16, v17
	v_max_i32_e32 v17, v8, v18
	v_min_i32_e32 v8, v8, v18
	v_max_i32_e32 v18, v10, v15
	v_min_i32_e32 v10, v10, v15
	v_min_i32_e32 v15, v4, v6
	v_min_i32_e32 v118, v117, v5
	v_min_i32_e32 v119, v12, v9
	v_min_i32_e32 v120, v11, v19
	v_min_i32_e32 v121, v7, v16
	v_min_i32_e32 v122, v13, v14
	v_min_i32_e32 v123, v8, v10
	v_min_i32_e32 v124, v17, v18
	v_max_i32_e32 v2, v2, v15
	v_max3_i32 v4, v102, v4, v6
	v_max_i32_e32 v6, v103, v118
	v_max3_i32 v5, v104, v117, v5
	v_max_i32_e32 v15, v105, v119
	v_max3_i32 v9, v106, v12, v9
	v_max_i32_e32 v12, v107, v120
	v_max3_i32 v11, v108, v11, v19
	v_max_i32_e32 v19, v109, v121
	v_max3_i32 v7, v110, v7, v16
	v_max_i32_e32 v16, v111, v122
	v_max3_i32 v13, v112, v13, v14
	v_max_i32_e32 v14, v113, v123
	v_max3_i32 v8, v114, v8, v10
	v_max_i32_e32 v10, v115, v124
	v_max3_i32 v17, v116, v17, v18
	v_max_i32_e32 v18, v2, v19
	v_min_i32_e32 v2, v2, v19
	v_max_i32_e32 v19, v4, v7
	v_min_i32_e32 v4, v4, v7
	v_max_i32_e32 v7, v6, v16
	v_min_i32_e32 v6, v6, v16
	v_max_i32_e32 v16, v5, v13
	v_min_i32_e32 v5, v5, v13
	v_max_i32_e32 v13, v15, v14
	v_min_i32_e32 v14, v15, v14
	v_max_i32_e32 v15, v9, v8
	v_min_i32_e32 v8, v9, v8
	v_max_i32_e32 v9, v12, v10
	v_min_i32_e32 v10, v12, v10
	v_max_i32_e32 v12, v11, v17
	v_min_i32_e32 v11, v11, v17
	v_max_i32_e32 v17, v18, v13
	v_min_i32_e32 v13, v18, v13
	v_max_i32_e32 v18, v19, v15
	v_min_i32_e32 v15, v19, v15
	v_max_i32_e32 v19, v7, v9
	v_min_i32_e32 v7, v7, v9
	v_max_i32_e32 v9, v16, v12
	v_min_i32_e32 v12, v16, v12
	v_max_i32_e32 v16, v2, v14
	v_min_i32_e32 v2, v2, v14
	v_max_i32_e32 v14, v4, v8
	v_min_i32_e32 v4, v4, v8
	v_max_i32_e32 v8, v6, v10
	v_min_i32_e32 v6, v6, v10
	v_max_i32_e32 v10, v5, v11
	v_min_i32_e32 v5, v5, v11
	v_max_i32_e32 v11, v17, v19
	v_min_i32_e32 v17, v17, v19
	v_max_i32_e32 v19, v18, v9
	v_min_i32_e32 v9, v18, v9
	v_max_i32_e32 v18, v13, v7
	v_min_i32_e32 v7, v13, v7
	v_max_i32_e32 v13, v15, v12
	v_min_i32_e32 v12, v15, v12
	v_max_i32_e32 v15, v16, v8
	v_min_i32_e32 v8, v16, v8
	v_max_i32_e32 v16, v14, v10
	v_min_i32_e32 v10, v14, v10
	v_max_i32_e32 v14, v2, v6
	v_min_i32_e32 v6, v2, v6
	v_max_i32_e32 v114, v4, v5
	v_min_i32_e32 v4, v4, v5
	v_max_i32_e32 v2, v11, v19
	v_min_i32_e32 v102, v11, v19
	v_max_i32_e32 v103, v17, v9
	v_min_i32_e32 v104, v17, v9
	v_max_i32_e32 v105, v18, v13
	v_min_i32_e32 v106, v18, v13
	v_max_i32_e32 v107, v7, v12
	v_min_i32_e32 v108, v7, v12
	v_max_i32_e32 v109, v15, v16
	v_min_i32_e32 v110, v15, v16
	v_max_i32_e32 v111, v8, v10
	v_min_i32_e32 v112, v8, v10
	v_max_i32_e32 v113, v14, v114
	v_min_i32_e32 v114, v14, v114
	v_max_i32_e32 v115, v6, v4
	v_min_i32_e32 v116, v6, v4
	s_cbranch_scc1 .LBB0_517
; template <int MASK> __device__ __forceinline__ int f2key(float f, int payload) { int b = __float_as_int(f); b ^= (b >> 31) & 0x7fffffff; return (b & ~MASK) | payload; }
; template <int MASK> __device__ __forceinline__ float key2f(int k) { int b = k & ~MASK; b ^= (b >> 31) & 0x7fffffff; return __int_as_float(b); }
; __device__ __forceinline__ void partner_merge16(int (&k)[16], int hi) {
;     int pr[16];
; #pragma unroll
;     for (int i = 0; i < 16; ++i) { auto rr = __builtin_amdgcn_permlane32_swap((unsigned)k[i], (unsigned)k[i], false, false); pr[i] = hi ? (int)rr[0] : (int)rr[1]; }
; #pragma unroll
;     for (int i = 0; i < 16; ++i) k[i] = imax(k[i], pr[15 - i]);
;     bitonic_merge16<true>(k);
; __device__ __forceinline__ void route_mfma(const bf16_t* __restrict__ PQb, const bf16_t* __restrict__ SKb, int* __restrict__ IDX, float* __restrict__ G) {
;     ...
;             partner_merge16(t0, hi);
; #pragma unroll
;             for (int i = 0; i < 16; ++i) sv[p][i] = t0[i];
; #pragma unroll
;             for (int q4 = 0; q4 < 4; ++q4)
;                 *(unsigned*)(myslot + p * 16 + q4 * 4) = (unsigned)(t0[4 * q4] & 0x7f) | ((unsigned)(t0[4 * q4 + 1] & 0x7f) << 8) | ((unsigned)(t0[4 * q4 + 2] & 0x7f) << 16) | ((unsigned)(t0[4 * q4 + 3] & 0x7f) << 24);
;         }
;         float f0[16], f1[16];
; #pragma unroll
;         for (int i = 0; i < 16; ++i) { f0[i] = key2f<0x7f>(sv[0][i]); f1[i] = key2f<0x7f>(sv[1][i]); }
;         int cd[32];
;         {
;             constexpr int PA[50] = {0,0,0,0,0,0,0,0,0,0,0,0,0,0,0,0, 1,1,1,1,1,1,1,1, 2,2,2,2,2, 3,3,3,3, 4,4,4, 5,5, 6,6, 7,7, 8,9,10,11,12,13,14,15};
;             constexpr int PB[50] = {0,1,2,3,4,5,6,7,8,9,10,11,12,13,14,15, 0,1,2,3,4,5,6,7, 0,1,2,3,4, 0,1,2,3, 0,1,2, 0,1, 0,1, 0,1, 0,0,0,0,0,0,0,0};
; #pragma unroll
;             for (int q = 0; q < 25; ++q) {
;                 const int a0 = PA[2 * q], b0 = PB[2 * q], a1 = PA[2 * q + 1], b1 = PB[2 * q + 1];
;                 const float s0 = f0[a0] + f1[b0], s1 = f0[a1] + f1[b1];
;                 cd[q] = hi ? f2key<0xff>(s1, a1 * 16 + b1) : f2key<0xff>(s0, a0 * 16 + b0);
	v_mov_b32_e32 v4, v2
	v_mov_b32_e32 v5, v2
	s_nop 1
	v_permlane32_swap_b32_e32 v4, v5
	v_cndmask_b32_e64 v4, v4, v5, s[42:43]
	v_mov_b32_e32 v5, v102
	v_mov_b32_e32 v6, v102
	s_nop 1
	v_permlane32_swap_b32_e32 v5, v6
	v_cndmask_b32_e64 v5, v5, v6, s[42:43]
	v_mov_b32_e32 v6, v103
	v_mov_b32_e32 v7, v103
	s_nop 1
	v_permlane32_swap_b32_e32 v6, v7
	v_cndmask_b32_e64 v6, v6, v7, s[42:43]
	v_mov_b32_e32 v7, v104
	v_mov_b32_e32 v8, v104
	s_nop 1
	v_permlane32_swap_b32_e32 v7, v8
	v_cndmask_b32_e64 v7, v7, v8, s[42:43]
	v_mov_b32_e32 v8, v105
	v_mov_b32_e32 v9, v105
	s_nop 1
	v_permlane32_swap_b32_e32 v8, v9
	v_cndmask_b32_e64 v8, v8, v9, s[42:43]
	v_mov_b32_e32 v9, v106
	v_mov_b32_e32 v10, v106
	s_nop 1
	v_permlane32_swap_b32_e32 v9, v10
	v_cndmask_b32_e64 v9, v9, v10, s[42:43]
	v_mov_b32_e32 v10, v107
	v_mov_b32_e32 v11, v107
	s_nop 1
	v_permlane32_swap_b32_e32 v10, v11
	v_cndmask_b32_e64 v10, v10, v11, s[42:43]
	v_mov_b32_e32 v11, v108
	v_mov_b32_e32 v12, v108
	s_nop 1
	v_permlane32_swap_b32_e32 v11, v12
	v_cndmask_b32_e64 v11, v11, v12, s[42:43]
	v_mov_b32_e32 v12, v109
	v_mov_b32_e32 v13, v109
	s_nop 1
	v_permlane32_swap_b32_e32 v12, v13
	v_cndmask_b32_e64 v12, v12, v13, s[42:43]
	v_mov_b32_e32 v13, v110
	v_mov_b32_e32 v14, v110
	s_nop 1
	v_permlane32_swap_b32_e32 v13, v14
	v_cndmask_b32_e64 v13, v13, v14, s[42:43]
	v_mov_b32_e32 v14, v111
	v_mov_b32_e32 v15, v111
	s_nop 1
	v_permlane32_swap_b32_e32 v14, v15
	v_cndmask_b32_e64 v14, v14, v15, s[42:43]
	v_mov_b32_e32 v15, v112
	v_mov_b32_e32 v16, v112
	s_nop 1
	v_permlane32_swap_b32_e32 v15, v16
	v_cndmask_b32_e64 v15, v15, v16, s[42:43]
	v_mov_b32_e32 v16, v113
	v_mov_b32_e32 v17, v113
	s_nop 1
	v_permlane32_swap_b32_e32 v16, v17
	v_cndmask_b32_e64 v16, v16, v17, s[42:43]
	v_mov_b32_e32 v17, v114
	v_mov_b32_e32 v18, v114
	s_nop 1
	v_permlane32_swap_b32_e32 v17, v18
	v_cndmask_b32_e64 v17, v17, v18, s[42:43]
	v_mov_b32_e32 v18, v115
	v_mov_b32_e32 v19, v115
	s_nop 1
	v_permlane32_swap_b32_e32 v18, v19
	v_cndmask_b32_e64 v18, v18, v19, s[42:43]
	v_mov_b32_e32 v19, v116
	v_mov_b32_e32 v20, v116
	s_nop 1
	v_permlane32_swap_b32_e32 v19, v20
	v_cndmask_b32_e64 v19, v19, v20, s[42:43]
	v_max_i32_e32 v2, v2, v19
	v_max_i32_e32 v18, v102, v18
	v_max_i32_e32 v17, v103, v17
	v_max_i32_e32 v16, v104, v16
	v_max_i32_e32 v15, v105, v15
	v_max_i32_e32 v14, v106, v14
	v_max_i32_e32 v13, v107, v13
	v_max_i32_e32 v12, v108, v12
	v_max_i32_e32 v11, v109, v11
	v_max_i32_e32 v10, v110, v10
	v_max_i32_e32 v9, v111, v9
	v_max_i32_e32 v8, v112, v8
	v_max_i32_e32 v7, v113, v7
	v_max_i32_e32 v6, v114, v6
	v_max_i32_e32 v5, v115, v5
	v_max_i32_e32 v4, v116, v4
	v_max_i32_e32 v19, v2, v11
	v_min_i32_e32 v2, v2, v11
	v_max_i32_e32 v11, v18, v10
	v_min_i32_e32 v10, v18, v10
	v_max_i32_e32 v18, v17, v9
	v_min_i32_e32 v9, v17, v9
	v_max_i32_e32 v17, v16, v8
	v_min_i32_e32 v8, v16, v8
	v_max_i32_e32 v16, v15, v7
	v_min_i32_e32 v7, v15, v7
	v_max_i32_e32 v15, v14, v6
	v_min_i32_e32 v6, v14, v6
	v_max_i32_e32 v14, v13, v5
	v_min_i32_e32 v5, v13, v5
	v_max_i32_e32 v13, v12, v4
	v_min_i32_e32 v4, v12, v4
	v_max_i32_e32 v12, v19, v16
	v_min_i32_e32 v16, v19, v16
	v_max_i32_e32 v19, v11, v15
	v_min_i32_e32 v11, v11, v15
	v_max_i32_e32 v15, v18, v14
	v_min_i32_e32 v14, v18, v14
	v_max_i32_e32 v18, v17, v13
	v_min_i32_e32 v13, v17, v13
	v_max_i32_e32 v17, v2, v7
	v_min_i32_e32 v2, v2, v7
	v_max_i32_e32 v7, v10, v6
	v_min_i32_e32 v6, v10, v6
	v_max_i32_e32 v10, v9, v5
	v_min_i32_e32 v5, v9, v5
	v_max_i32_e32 v9, v8, v4
	v_min_i32_e32 v4, v8, v4
	v_max_i32_e32 v8, v12, v15
	v_min_i32_e32 v21, v12, v15
	v_max_i32_e32 v15, v16, v14
	v_min_i32_e32 v14, v16, v14
	v_max_i32_e32 v16, v11, v13
	v_max_i32_e32 v31, v19, v18
	v_min_i32_e32 v18, v19, v18
	v_min_i32_e32 v11, v11, v13
	v_max_i32_e32 v19, v7, v9
	v_min_i32_e32 v7, v7, v9
	v_max_i32_e32 v9, v2, v5
	v_min_i32_e32 v2, v2, v5
	v_max_i32_e32 v5, v6, v4
	v_max_i32_e32 v12, v15, v16
	v_min_i32_e32 v23, v15, v16
	v_max_i32_e32 v13, v17, v10
	v_min_i32_e32 v17, v17, v10
	v_min_i32_e32 v4, v6, v4
	v_max_i32_e32 v28, v14, v11
	v_min_i32_e32 v10, v14, v11
	v_max_i32_e32 v29, v9, v5
	v_min_i32_e32 v24, v9, v5
	v_and_b32_e32 v5, 0x7f, v12
	v_lshlrev_b32_e32 v6, 8, v23
	s_movk_i32 s12, 0x7f00
	v_max_i32_e32 v27, v17, v7
	v_min_i32_e32 v22, v17, v7
	v_and_or_b32 v5, v6, s12, v5
	v_lshlrev_b32_e32 v6, 16, v28
	v_lshlrev_b32_e32 v7, 24, v10
	v_max_i32_e32 v26, v13, v19
	v_min_i32_e32 v20, v13, v19
	v_and_b32_e32 v6, 0x7f0000, v6
	v_and_b32_e32 v7, 0x7f000000, v7
	v_or3_b32 v15, v5, v6, v7
	v_and_b32_e32 v5, 0x7f, v26
	v_lshlrev_b32_e32 v6, 8, v20
	v_and_or_b32 v5, v6, s12, v5
	v_lshlrev_b32_e32 v6, 16, v27
	v_lshlrev_b32_e32 v7, 24, v22
	v_and_b32_e32 v6, 0x7f0000, v6
	v_and_b32_e32 v7, 0x7f000000, v7
	v_max_i32_e32 v30, v2, v4
	v_min_i32_e32 v25, v2, v4
	v_or3_b32 v16, v5, v6, v7
	v_and_b32_e32 v5, 0x7f, v29
	v_lshlrev_b32_e32 v6, 8, v24
	v_and_or_b32 v5, v6, s12, v5
	v_lshlrev_b32_e32 v6, 16, v30
	v_lshlrev_b32_e32 v7, 24, v25
	v_and_b32_e32 v6, 0x7f0000, v6
	v_and_b32_e32 v7, 0x7f000000, v7
	v_max_i32_e32 v33, v21, v18
	v_or3_b32 v17, v5, v6, v7
	v_and_b32_e32 v5, 0xffffff80, v1
	v_ashrrev_i32_e32 v1, 31, v1
	s_brev_b32 s15, -2
	v_bitop3_b32 v6, v1, v5, s15 bitop3:0x6c
	v_and_b32_e32 v1, 0xffffff80, v33
	v_ashrrev_i32_e32 v5, 31, v33
	v_max_i32_e32 v32, v8, v31
	v_bitop3_b32 v9, v5, v1, s15 bitop3:0x6c
	v_min_i32_e32 v1, v8, v31
	v_and_b32_e32 v2, 0x7f, v32
	v_min_i32_e32 v5, v21, v18
	v_lshlrev_b32_e32 v7, 8, v1
	v_lshlrev_b32_e32 v4, 16, v33
	v_and_or_b32 v2, v7, s12, v2
	v_lshlrev_b32_e32 v7, 24, v5
	v_and_b32_e32 v4, 0x7f0000, v4
	v_and_b32_e32 v7, 0x7f000000, v7
	v_or3_b32 v14, v2, v4, v7
	v_and_b32_e32 v2, 0xffffff80, v1
	v_and_b32_e32 v4, 0xffffff80, v5
	v_ashrrev_i32_e32 v1, 31, v1
	v_ashrrev_i32_e32 v5, 31, v5
	v_and_b32_e32 v1, 0x7fffffff, v1
	v_and_b32_e32 v5, 0x7fffffff, v5
	v_xor_b32_e32 v1, v1, v2
	v_xor_b32_e32 v2, v5, v4
	v_ashrrev_i32_e32 v5, 31, v32
	v_and_b32_e32 v8, 0x7fffffff, v5
	v_ashrrev_i32_e32 v5, 31, v101
	v_and_b32_e32 v4, 0xffffff80, v101
	v_and_b32_e32 v7, 0xffffff80, v32
	v_and_b32_e32 v5, 0x7fffffff, v5
	v_xor_b32_e32 v5, v5, v4
	v_xor_b32_e32 v4, v8, v7
	ds_write_b128 v69, v[14:17] offset:16
	s_and_saveexec_b64 s[12:13], s[44:45]
	s_xor_b64 s[12:13], exec, s[12:13]
	s_cbranch_execz .LBB0_520
; template <int MASK> __device__ __forceinline__ int f2key(float f, int payload) { int b = __float_as_int(f); b ^= (b >> 31) & 0x7fffffff; return (b & ~MASK) | payload; }
; template <int MASK> __device__ __forceinline__ float key2f(int k) { int b = k & ~MASK; b ^= (b >> 31) & 0x7fffffff; return __int_as_float(b); }
; __device__ __forceinline__ void route_mfma(const bf16_t* __restrict__ PQb, const bf16_t* __restrict__ SKb, int* __restrict__ IDX, float* __restrict__ G) {
;     ...
;         float f0[16], f1[16];
; #pragma unroll
;         for (int i = 0; i < 16; ++i) { f0[i] = key2f<0x7f>(sv[0][i]); f1[i] = key2f<0x7f>(sv[1][i]); }
;         int cd[32];
;         {
;             constexpr int PA[50] = {0,0,0,0,0,0,0,0,0,0,0,0,0,0,0,0, 1,1,1,1,1,1,1,1, 2,2,2,2,2, 3,3,3,3, 4,4,4, 5,5, 6,6, 7,7, 8,9,10,11,12,13,14,15};
;             constexpr int PB[50] = {0,1,2,3,4,5,6,7,8,9,10,11,12,13,14,15, 0,1,2,3,4,5,6,7, 0,1,2,3,4, 0,1,2,3, 0,1,2, 0,1, 0,1, 0,1, 0,0,0,0,0,0,0,0};
; #pragma unroll
;             for (int q = 0; q < 25; ++q) {
;                 const int a0 = PA[2 * q], b0 = PB[2 * q], a1 = PA[2 * q + 1], b1 = PB[2 * q + 1];
;                 const float s0 = f0[a0] + f1[b0], s1 = f0[a1] + f1[b1];
;                 cd[q] = hi ? f2key<0xff>(s1, a1 * 16 + b1) : f2key<0xff>(s0, a0 * 16 + b0);
	v_ashrrev_i32_e32 v7, 31, v100
	v_and_b32_e32 v8, 0xffffff80, v100
	v_bitop3_b32 v7, v7, v8, s15 bitop3:0x6c
	v_ashrrev_i32_e32 v8, 31, v99
	v_and_b32_e32 v11, 0xffffff80, v99
	v_bitop3_b32 v14, v8, v11, s15 bitop3:0x6c
	v_ashrrev_i32_e32 v8, 31, v98
	v_and_b32_e32 v11, 0xffffff80, v98
	v_bitop3_b32 v15, v8, v11, s15 bitop3:0x6c
	v_ashrrev_i32_e32 v8, 31, v97
	v_and_b32_e32 v11, 0xffffff80, v97
	v_bitop3_b32 v8, v8, v11, s15 bitop3:0x6c
	v_ashrrev_i32_e32 v11, 31, v10
	v_and_b32_e32 v10, 0xffffff80, v10
	v_bitop3_b32 v10, v11, v10, s15 bitop3:0x6c
	v_ashrrev_i32_e32 v11, 31, v23
	v_and_b32_e32 v13, 0xffffff80, v23
	v_bitop3_b32 v11, v11, v13, s15 bitop3:0x6c
	v_ashrrev_i32_e32 v13, 31, v25
	v_and_b32_e32 v16, 0xffffff80, v25
	v_bitop3_b32 v17, v13, v16, s15 bitop3:0x6c
	v_ashrrev_i32_e32 v13, 31, v24
	v_and_b32_e32 v16, 0xffffff80, v24
	v_bitop3_b32 v18, v13, v16, s15 bitop3:0x6c
	v_ashrrev_i32_e32 v13, 31, v22
	v_and_b32_e32 v16, 0xffffff80, v22
	v_bitop3_b32 v19, v13, v16, s15 bitop3:0x6c
	v_ashrrev_i32_e32 v13, 31, v20
	v_and_b32_e32 v16, 0xffffff80, v20
	v_bitop3_b32 v21, v13, v16, s15 bitop3:0x6c
	v_add_f32_e32 v13, v1, v6
	v_ashrrev_i32_e32 v16, 31, v13
	v_and_b32_e32 v16, 0x7fffff00, v16
	v_and_b32_e32 v13, 0xffffff00, v13
	v_bitop3_b32 v16, v16, 1, v13 bitop3:0xde
	v_mov_b32_e32 v13, v1
	v_mov_b32_e32 v1, v9

; #define GAS __attribute__((address_space(1)))
; template <int MASK> __device__ __forceinline__ int f2key(float f, int payload) { int b = __float_as_int(f); b ^= (b >> 31) & 0x7fffffff; return (b & ~MASK) | payload; }
; __device__ __forceinline__ void route_mfma(const bf16_t* __restrict__ PQb, const bf16_t* __restrict__ SKb, int* __restrict__ IDX, float* __restrict__ G) {
;     ...
; #pragma unroll 1
;             for (int blk = 0; blk < 4; ++blk) {
;                 f32x16 acc;
; #pragma unroll
;                 for (int r = 0; r < 16; ++r) acc[r] = 0.f;
; #pragma unroll
;                 for (int s = 0; s < 8; ++s)
;                     acc = __builtin_amdgcn_mfma_f32_32x32x16_bf16(*(const GAS bf16x8*)(kp + (size_t)blk * 32 * 128 + 16 * s), qf[s], acc, 0, 0, 0);
;                 int nk[16];
;                 const int pay = (32 * blk) | (hi << 2);
; #pragma unroll
;                 for (int r = 0; r < 16; ++r) nk[r] = f2key<0x7f>(acc[r], pay | ((r & 3) + 8 * (r >> 2)));
;                 bitonic_sort16<false>(nk);
; #pragma unroll
;                 for (int i = 0; i < 16; ++i) t0[i] = imax(t0[i], nk[i]);
;                 bitonic_merge16<true>(t0);
;             }
.Lrt_skip_3:
	v_add_u32_e32 v104, s12, v70
	s_add_i32 s12, s12, 32
	s_cmpk_lg_i32 s12, 0x80
	s_nop 8
	v_ashrrev_i32_e32 v103, 31, v4
	v_and_b32_e32 v103, 0x7fffff80, v103
	v_and_b32_e32 v4, 0xffffff80, v4
	v_xad_u32 v4, v103, v4, v104
	v_ashrrev_i32_e32 v103, 31, v5
	v_and_b32_e32 v5, 0xffffff80, v5
	v_bitop3_b32 v5, v103, v5, s3 bitop3:0x6c
	v_ashrrev_i32_e32 v103, 31, v6
	v_and_b32_e32 v6, 0xffffff80, v6
	v_bitop3_b32 v6, v103, v6, s3 bitop3:0x6c
	v_ashrrev_i32_e32 v103, 31, v7
	v_and_b32_e32 v7, 0xffffff80, v7
	v_bitop3_b32 v7, v103, v7, s3 bitop3:0x6c
	v_ashrrev_i32_e32 v103, 31, v8
	v_and_b32_e32 v8, 0xffffff80, v8
	v_bitop3_b32 v8, v103, v8, s3 bitop3:0x6c
	v_ashrrev_i32_e32 v103, 31, v9
	v_and_b32_e32 v9, 0xffffff80, v9
	v_bitop3_b32 v9, v103, v9, s3 bitop3:0x6c
	v_ashrrev_i32_e32 v103, 31, v10
	v_and_b32_e32 v10, 0xffffff80, v10
	v_bitop3_b32 v10, v103, v10, s3 bitop3:0x6c
	v_ashrrev_i32_e32 v103, 31, v11
	v_and_b32_e32 v11, 0xffffff80, v11
	v_bitop3_b32 v11, v103, v11, s3 bitop3:0x6c
	v_ashrrev_i32_e32 v103, 31, v12
	v_and_b32_e32 v12, 0xffffff80, v12
	v_bitop3_b32 v12, v103, v12, s3 bitop3:0x6c
	v_ashrrev_i32_e32 v103, 31, v13
	v_and_b32_e32 v13, 0xffffff80, v13
	v_bitop3_b32 v13, v103, v13, s3 bitop3:0x6c
	v_ashrrev_i32_e32 v103, 31, v14
	v_and_b32_e32 v14, 0xffffff80, v14
	v_bitop3_b32 v14, v103, v14, s3 bitop3:0x6c
	v_ashrrev_i32_e32 v103, 31, v15
	v_and_b32_e32 v15, 0xffffff80, v15
	v_bitop3_b32 v15, v103, v15, s3 bitop3:0x6c
	v_ashrrev_i32_e32 v103, 31, v16
	v_and_b32_e32 v16, 0xffffff80, v16
	v_bitop3_b32 v16, v103, v16, s3 bitop3:0x6c
	v_ashrrev_i32_e32 v103, 31, v17
	v_and_b32_e32 v17, 0xffffff80, v17
	v_bitop3_b32 v17, v103, v17, s3 bitop3:0x6c
	v_ashrrev_i32_e32 v103, 31, v18
	v_and_b32_e32 v18, 0xffffff80, v18
	v_bitop3_b32 v18, v103, v18, s3 bitop3:0x6c
	v_ashrrev_i32_e32 v103, 31, v19
	v_and_b32_e32 v19, 0xffffff80, v19
	v_bitop3_b32 v19, v103, v19, s3 bitop3:0x6c
	v_add3_u32 v5, v104, v5, 1
	v_add3_u32 v6, v104, v6, 2
	v_add3_u32 v7, v104, v7, 3
	v_add3_u32 v8, v104, v8, 8
	v_add3_u32 v9, v104, v9, 9
	v_add3_u32 v10, v104, v10, 10
	v_add3_u32 v11, v104, v11, 11
	v_add3_u32 v12, v104, v12, 16
	v_add3_u32 v13, v104, v13, 17
	v_add3_u32 v14, v104, v14, 18
	v_add3_u32 v15, v104, v15, 19
	v_add3_u32 v16, v104, v16, 24
	v_add3_u32 v17, v104, v17, 25
	v_add3_u32 v18, v104, v18, 26
	v_add3_u32 v19, v104, v19, 27
	v_max_i32_e32 v103, v4, v5
	v_min_i32_e32 v4, v4, v5
	v_max_i32_e32 v5, v6, v7
	v_min_i32_e32 v6, v6, v7
	v_max_i32_e32 v7, v8, v9
	v_min_i32_e32 v8, v8, v9
	v_max_i32_e32 v9, v10, v11
	v_min_i32_e32 v10, v10, v11
	v_max_i32_e32 v11, v12, v13
	v_min_i32_e32 v12, v12, v13
	v_max_i32_e32 v13, v14, v15
	v_min_i32_e32 v14, v14, v15
	v_max_i32_e32 v15, v16, v17
	v_min_i32_e32 v16, v16, v17
	v_max_i32_e32 v17, v18, v19
	v_min_i32_e32 v18, v18, v19
	v_max_i32_e32 v19, v4, v5
	v_min_i32_e32 v4, v4, v5
	v_max_i32_e32 v5, v103, v6
	v_min_i32_e32 v6, v103, v6
	v_max_i32_e32 v103, v8, v9
	v_min_i32_e32 v8, v8, v9
	v_max_i32_e32 v9, v7, v10
	v_min_i32_e32 v7, v7, v10
	v_max_i32_e32 v10, v12, v13
	v_min_i32_e32 v12, v12, v13
	v_max_i32_e32 v13, v11, v14
	v_min_i32_e32 v11, v11, v14
	v_max_i32_e32 v14, v16, v17
	v_min_i32_e32 v16, v16, v17
	v_max_i32_e32 v17, v15, v18
	v_min_i32_e32 v15, v15, v18
	v_max_i32_e32 v18, v4, v6
	v_min_i32_e32 v4, v4, v6
	v_max_i32_e32 v6, v19, v5
	v_min_i32_e32 v5, v19, v5
	v_max_i32_e32 v19, v103, v9
	v_min_i32_e32 v9, v103, v9
	v_max_i32_e32 v103, v8, v7
	v_min_i32_e32 v7, v8, v7
	v_max_i32_e32 v8, v12, v11
	v_min_i32_e32 v11, v12, v11
	v_max_i32_e32 v12, v10, v13
	v_min_i32_e32 v10, v10, v13
	v_max_i32_e32 v13, v14, v17
	v_min_i32_e32 v14, v14, v17
	v_max_i32_e32 v17, v16, v15
	v_min_i32_e32 v15, v16, v15
	v_max_i32_e32 v16, v4, v19
	v_min_i32_e32 v4, v4, v19
	v_max_i32_e32 v19, v18, v9
	v_min_i32_e32 v9, v18, v9
	v_max_i32_e32 v18, v5, v103
	v_min_i32_e32 v5, v5, v103
	v_max_i32_e32 v103, v6, v7
	v_min_i32_e32 v6, v6, v7
	v_max_i32_e32 v7, v11, v13
	v_min_i32_e32 v11, v11, v13
	v_max_i32_e32 v13, v8, v14
	v_min_i32_e32 v8, v8, v14
	v_max_i32_e32 v14, v10, v17
	v_min_i32_e32 v10, v10, v17
	v_max_i32_e32 v17, v12, v15
	v_min_i32_e32 v12, v12, v15
	v_max_i32_e32 v15, v4, v5
	v_min_i32_e32 v4, v4, v5
	v_max_i32_e32 v5, v9, v6
	v_min_i32_e32 v6, v9, v6
	v_max_i32_e32 v9, v16, v18
	v_min_i32_e32 v16, v16, v18
	v_max_i32_e32 v18, v19, v103
	v_min_i32_e32 v19, v19, v103
	v_max_i32_e32 v103, v7, v14
	v_min_i32_e32 v7, v7, v14
	v_max_i32_e32 v14, v13, v17
	v_min_i32_e32 v13, v13, v17
	v_max_i32_e32 v17, v11, v10
	v_min_i32_e32 v10, v11, v10
	v_max_i32_e32 v11, v8, v12
	v_min_i32_e32 v8, v8, v12
	v_max_i32_e32 v12, v4, v6
	v_min_i32_e32 v4, v4, v6
	v_max_i32_e32 v6, v15, v5
	v_min_i32_e32 v5, v15, v5
	v_max_i32_e32 v15, v16, v19
	v_min_i32_e32 v16, v16, v19
	v_max_i32_e32 v19, v9, v18
	v_min_i32_e32 v9, v9, v18
	v_max_i32_e32 v18, v103, v14
	v_min_i32_e32 v14, v103, v14
	v_max_i32_e32 v103, v7, v13
	v_min_i32_e32 v7, v7, v13
	v_max_i32_e32 v13, v17, v11
	v_min_i32_e32 v11, v17, v11
	v_max_i32_e32 v17, v10, v8
	v_min_i32_e32 v8, v10, v8
	v_max_i32_e32 v10, v4, v18
	v_min_i32_e32 v4, v4, v18
	v_max_i32_e32 v18, v12, v14
	v_min_i32_e32 v12, v12, v14
	v_max_i32_e32 v14, v5, v103
	v_min_i32_e32 v5, v5, v103
	v_max_i32_e32 v103, v6, v7
	v_min_i32_e32 v6, v6, v7
	v_max_i32_e32 v7, v16, v13
	v_min_i32_e32 v13, v16, v13
	v_max_i32_e32 v16, v15, v11
	v_min_i32_e32 v11, v15, v11
	v_max_i32_e32 v15, v9, v17
	v_min_i32_e32 v9, v9, v17
	v_max_i32_e32 v17, v19, v8
	v_min_i32_e32 v8, v19, v8
	v_max_i32_e32 v19, v4, v13
	v_min_i32_e32 v4, v4, v13
	v_max_i32_e32 v13, v12, v11
	v_min_i32_e32 v11, v12, v11
	v_max_i32_e32 v12, v5, v9
; template <int MASK> __device__ __forceinline__ int f2key(float f, int payload) { int b = __float_as_int(f); b ^= (b >> 31) & 0x7fffffff; return (b & ~MASK) | payload; }
; template <bool DESC> __device__ __forceinline__ void bitonic_sort16(int (&k)[16]) {
; #pragma unroll
;     for (int size = 2; size <= 16; size <<= 1)
; #pragma unroll
;         for (int stride = size >> 1; stride > 0; stride >>= 1)
; #pragma unroll
;             for (int i = 0; i < 16; ++i) {
;                 const int j = i ^ stride;
;                 if (j > i) { const bool dd = (((i & size) == 0) == DESC);
;                              const int a = k[i], b = k[j], mx = imax(a, b), mn = imin(a, b); k[i] = dd ? mx : mn; k[j] = dd ? mn : mx; }
;             }
; }
; template <bool DESC> __device__ __forceinline__ void bitonic_merge16(int (&k)[16]) {
; #pragma unroll
;     for (int stride = 8; stride > 0; stride >>= 1)
; #pragma unroll
;         for (int i = 0; i < 16; ++i) {
;             const int j = i ^ stride;
;             if (j > i) { const int a = k[i], b = k[j], mx = imax(a, b), mn = imin(a, b); k[i] = DESC ? mx : mn; k[j] = DESC ? mn : mx; }
;         }
; }
; __device__ __forceinline__ void route_mfma(const bf16_t* __restrict__ PQb, const bf16_t* __restrict__ SKb, int* __restrict__ IDX, float* __restrict__ G) {
;     ...
;                 for (int r = 0; r < 16; ++r) nk[r] = f2key<0x7f>(acc[r], pay | ((r & 3) + 8 * (r >> 2)));
;                 bitonic_sort16<false>(nk);
; #pragma unroll
;                 for (int i = 0; i < 16; ++i) t0[i] = imax(t0[i], nk[i]);
;                 bitonic_merge16<true>(t0);
	v_min_i32_e32 v5, v5, v9
	v_max_i32_e32 v9, v6, v8
	v_min_i32_e32 v6, v6, v8
	v_max_i32_e32 v8, v10, v7
	v_min_i32_e32 v7, v10, v7
	v_max_i32_e32 v10, v18, v16
	v_min_i32_e32 v16, v18, v16
	v_max_i32_e32 v18, v14, v15
	v_min_i32_e32 v14, v14, v15
	v_max_i32_e32 v15, v103, v17
	v_min_i32_e32 v17, v103, v17
	v_max_i32_e32 v103, v4, v5
	v_min_i32_e32 v4, v4, v5
	v_max_i32_e32 v5, v11, v6
	v_min_i32_e32 v6, v11, v6
	v_max_i32_e32 v11, v19, v12
	v_min_i32_e32 v12, v19, v12
	v_max_i32_e32 v19, v13, v9
	v_min_i32_e32 v9, v13, v9
	v_max_i32_e32 v13, v7, v14
	v_min_i32_e32 v7, v7, v14
	v_max_i32_e32 v14, v16, v17
	v_min_i32_e32 v16, v16, v17
	v_max_i32_e32 v17, v8, v18
	v_min_i32_e32 v8, v8, v18
	v_max_i32_e32 v18, v10, v15
	v_min_i32_e32 v10, v10, v15
	v_min_i32_e32 v15, v4, v6
	v_min_i32_e32 v104, v103, v5
	v_min_i32_e32 v105, v12, v9
	v_min_i32_e32 v106, v11, v19
	v_min_i32_e32 v107, v7, v16
	v_min_i32_e32 v108, v13, v14
	v_min_i32_e32 v109, v8, v10
	v_min_i32_e32 v110, v17, v18
	v_max_i32_e32 v1, v1, v15
	v_max3_i32 v2, v2, v4, v6
	v_max_i32_e32 v4, v89, v104
	v_max3_i32 v5, v90, v103, v5
	v_max_i32_e32 v6, v91, v105
	v_max3_i32 v9, v92, v12, v9
	v_max_i32_e32 v12, v93, v106
	v_max3_i32 v11, v94, v11, v19
	v_max_i32_e32 v15, v95, v107
	v_max3_i32 v7, v96, v7, v16
	v_max_i32_e32 v16, v97, v108
	v_max3_i32 v13, v98, v13, v14
	v_max_i32_e32 v14, v99, v109
	v_max3_i32 v8, v100, v8, v10
	v_max_i32_e32 v10, v101, v110
	v_max3_i32 v17, v102, v17, v18
	v_max_i32_e32 v18, v1, v15
	v_min_i32_e32 v1, v1, v15
	v_max_i32_e32 v15, v2, v7
	v_min_i32_e32 v2, v2, v7
	v_max_i32_e32 v7, v4, v16
	v_min_i32_e32 v4, v4, v16
	v_max_i32_e32 v16, v5, v13
	v_min_i32_e32 v5, v5, v13
	v_max_i32_e32 v13, v6, v14
	v_min_i32_e32 v6, v6, v14
	v_max_i32_e32 v14, v9, v8
	v_min_i32_e32 v8, v9, v8
	v_max_i32_e32 v9, v12, v10
	v_min_i32_e32 v10, v12, v10
	v_max_i32_e32 v12, v11, v17
	v_min_i32_e32 v11, v11, v17
	v_max_i32_e32 v17, v18, v13
	v_min_i32_e32 v13, v18, v13
	v_max_i32_e32 v18, v15, v14
	v_min_i32_e32 v14, v15, v14
	v_max_i32_e32 v15, v7, v9
	v_min_i32_e32 v7, v7, v9
	v_max_i32_e32 v9, v16, v12
	v_min_i32_e32 v12, v16, v12
	v_max_i32_e32 v16, v1, v6
	v_min_i32_e32 v1, v1, v6
	v_max_i32_e32 v6, v2, v8
	v_min_i32_e32 v2, v2, v8
	v_max_i32_e32 v8, v4, v10
	v_min_i32_e32 v4, v4, v10
	v_max_i32_e32 v10, v5, v11
	v_min_i32_e32 v5, v5, v11
	v_max_i32_e32 v11, v17, v15
	v_min_i32_e32 v15, v17, v15
	v_max_i32_e32 v17, v18, v9
	v_min_i32_e32 v9, v18, v9
	v_max_i32_e32 v18, v13, v7
	v_min_i32_e32 v7, v13, v7
	v_max_i32_e32 v13, v14, v12
	v_min_i32_e32 v12, v14, v12
	v_max_i32_e32 v14, v16, v8
	v_min_i32_e32 v8, v16, v8
	v_max_i32_e32 v16, v6, v10
	v_min_i32_e32 v6, v6, v10
	v_max_i32_e32 v10, v1, v4
	v_min_i32_e32 v4, v1, v4
	v_max_i32_e32 v19, v2, v5
	v_min_i32_e32 v5, v2, v5
	v_max_i32_e32 v1, v11, v17
	v_min_i32_e32 v2, v11, v17
	v_max_i32_e32 v89, v15, v9
	v_min_i32_e32 v90, v15, v9
	v_max_i32_e32 v91, v18, v13
	v_min_i32_e32 v92, v18, v13
	v_max_i32_e32 v93, v7, v12
	v_min_i32_e32 v94, v7, v12
	v_max_i32_e32 v95, v14, v16
	v_min_i32_e32 v96, v14, v16
	v_max_i32_e32 v97, v8, v6
	v_min_i32_e32 v98, v8, v6
	v_max_i32_e32 v99, v10, v19
	v_min_i32_e32 v100, v10, v19
	v_max_i32_e32 v101, v4, v5
	v_min_i32_e32 v102, v4, v5
	s_cbranch_scc1 .LBB0_1210
; #define GAS __attribute__((address_space(1)))
; __device__ __forceinline__ void partner_merge16(int (&k)[16], int hi) {
;     int pr[16];
; #pragma unroll
;     for (int i = 0; i < 16; ++i) { auto rr = __builtin_amdgcn_permlane32_swap((unsigned)k[i], (unsigned)k[i], false, false); pr[i] = hi ? (int)rr[0] : (int)rr[1]; }
; #pragma unroll
;     for (int i = 0; i < 16; ++i) k[i] = imax(k[i], pr[15 - i]);
;     bitonic_merge16<true>(k);
; __device__ __forceinline__ void route_mfma(const bf16_t* __restrict__ PQb, const bf16_t* __restrict__ SKb, int* __restrict__ IDX, float* __restrict__ G) {
;     ...
;         for (int p = 0; p < 2; ++p) {
;             const GAS bf16_t* qp = (const GAS bf16_t*)PQb + (size_t)tok * D + h * 256 + p * 128 + 8 * hi;
;             const GAS bf16_t* kp = (const GAS bf16_t*)SKb + ((size_t)(h * 2 + p) * 128 + c) * 128 + 8 * hi;
;             bf16x8 qf[8];
; #pragma unroll
;             for (int s = 0; s < 8; ++s) qf[s] = *(const GAS bf16x8*)(qp + 16 * s);
;             int t0[16];
; #pragma unroll
;             for (int i = 0; i < 16; ++i) t0[i] = (int)0x80000000;
; #pragma unroll 1
;             for (int blk = 0; blk < 4; ++blk) {
;                 f32x16 acc;
; #pragma unroll
;                 for (int r = 0; r < 16; ++r) acc[r] = 0.f;
; #pragma unroll
;                 for (int s = 0; s < 8; ++s)
;                     acc = __builtin_amdgcn_mfma_f32_32x32x16_bf16(*(const GAS bf16x8*)(kp + (size_t)blk * 32 * 128 + 16 * s), qf[s], acc, 0, 0, 0);
;                 int nk[16];
;                 const int pay = (32 * blk) | (hi << 2);
; #pragma unroll
;                 for (int r = 0; r < 16; ++r) nk[r] = f2key<0x7f>(acc[r], pay | ((r & 3) + 8 * (r >> 2)));
;                 bitonic_sort16<false>(nk);
; #pragma unroll
;                 for (int i = 0; i < 16; ++i) t0[i] = imax(t0[i], nk[i]);
;                 bitonic_merge16<true>(t0);
;             }
;             partner_merge16(t0, hi);
; #pragma unroll
;             for (int i = 0; i < 16; ++i) sv[p][i] = t0[i];
; #pragma unroll
;             for (int q4 = 0; q4 < 4; ++q4)
;                 *(unsigned*)(myslot + p * 16 + q4 * 4) = (unsigned)(t0[4 * q4] & 0x7f) | ((unsigned)(t0[4 * q4 + 1] & 0x7f) << 8) | ((unsigned)(t0[4 * q4 + 2] & 0x7f) << 16) | ((unsigned)(t0[4 * q4 + 3] & 0x7f) << 24);
	v_mov_b32_e32 v4, v1
	v_mov_b32_e32 v5, v1
	s_nop 1
	v_permlane32_swap_b32_e32 v4, v5
	v_cndmask_b32_e64 v4, v4, v5, s[40:41]
	v_mov_b32_e32 v5, v2
	v_mov_b32_e32 v6, v2
	s_nop 1
	v_permlane32_swap_b32_e32 v5, v6
	v_cndmask_b32_e64 v5, v5, v6, s[40:41]
	v_mov_b32_e32 v6, v89
	v_mov_b32_e32 v7, v89
	s_nop 1
	v_permlane32_swap_b32_e32 v6, v7
	v_cndmask_b32_e64 v6, v6, v7, s[40:41]
	v_mov_b32_e32 v7, v90
	v_mov_b32_e32 v8, v90
	s_nop 1
	v_permlane32_swap_b32_e32 v7, v8
	v_cndmask_b32_e64 v7, v7, v8, s[40:41]
	v_mov_b32_e32 v8, v91
	v_mov_b32_e32 v9, v91
	s_nop 1
	v_permlane32_swap_b32_e32 v8, v9
	v_cndmask_b32_e64 v8, v8, v9, s[40:41]
	v_mov_b32_e32 v9, v92
	v_mov_b32_e32 v10, v92
	s_nop 1
	v_permlane32_swap_b32_e32 v9, v10
	v_cndmask_b32_e64 v9, v9, v10, s[40:41]
	v_mov_b32_e32 v10, v93
	v_mov_b32_e32 v11, v93
	s_nop 1
	v_permlane32_swap_b32_e32 v10, v11
	v_cndmask_b32_e64 v10, v10, v11, s[40:41]
	v_mov_b32_e32 v11, v94
	v_mov_b32_e32 v12, v94
	s_nop 1
	v_permlane32_swap_b32_e32 v11, v12
	v_cndmask_b32_e64 v11, v11, v12, s[40:41]
	v_mov_b32_e32 v12, v95
	v_mov_b32_e32 v13, v95
	s_nop 1
	v_permlane32_swap_b32_e32 v12, v13
	v_cndmask_b32_e64 v12, v12, v13, s[40:41]
	v_mov_b32_e32 v13, v96
	v_mov_b32_e32 v14, v96
	s_nop 1
	v_permlane32_swap_b32_e32 v13, v14
	v_cndmask_b32_e64 v13, v13, v14, s[40:41]
	v_mov_b32_e32 v14, v97
	v_mov_b32_e32 v15, v97
	s_nop 1
	v_permlane32_swap_b32_e32 v14, v15
	v_cndmask_b32_e64 v14, v14, v15, s[40:41]
	v_mov_b32_e32 v15, v98
	v_mov_b32_e32 v16, v98
	s_nop 1
	v_permlane32_swap_b32_e32 v15, v16
	v_cndmask_b32_e64 v15, v15, v16, s[40:41]
	v_mov_b32_e32 v16, v99
	v_mov_b32_e32 v17, v99
	s_nop 1
	v_permlane32_swap_b32_e32 v16, v17
	v_cndmask_b32_e64 v16, v16, v17, s[40:41]
	v_mov_b32_e32 v17, v100
	v_mov_b32_e32 v18, v100
	s_nop 1
	v_permlane32_swap_b32_e32 v17, v18
	v_cndmask_b32_e64 v17, v17, v18, s[40:41]
	v_mov_b32_e32 v18, v101
	v_mov_b32_e32 v19, v101
	s_nop 1
	v_permlane32_swap_b32_e32 v18, v19
	v_cndmask_b32_e64 v18, v18, v19, s[40:41]
	v_mov_b32_e32 v19, v102
	v_mov_b32_e32 v20, v102
	s_nop 1
	v_permlane32_swap_b32_e32 v19, v20
	v_cndmask_b32_e64 v19, v19, v20, s[40:41]
	v_max_i32_e32 v1, v1, v19
	v_max_i32_e32 v2, v2, v18
	v_max_i32_e32 v17, v89, v17
	v_max_i32_e32 v16, v90, v16
	v_max_i32_e32 v15, v91, v15
	v_max_i32_e32 v14, v92, v14
	v_max_i32_e32 v13, v93, v13
	v_max_i32_e32 v12, v94, v12
	v_max_i32_e32 v11, v95, v11
	v_max_i32_e32 v10, v96, v10
	v_max_i32_e32 v9, v97, v9
	v_max_i32_e32 v8, v98, v8
	v_max_i32_e32 v7, v99, v7
	v_max_i32_e32 v6, v100, v6
	v_max_i32_e32 v5, v101, v5
	v_max_i32_e32 v4, v102, v4
	v_max_i32_e32 v18, v1, v11
	v_min_i32_e32 v1, v1, v11
	v_max_i32_e32 v11, v2, v10
	v_min_i32_e32 v2, v2, v10
	v_max_i32_e32 v10, v17, v9
	v_min_i32_e32 v9, v17, v9
	v_max_i32_e32 v17, v16, v8
	v_min_i32_e32 v8, v16, v8
	v_max_i32_e32 v16, v15, v7
	v_min_i32_e32 v7, v15, v7
	v_max_i32_e32 v15, v14, v6
	v_min_i32_e32 v6, v14, v6
	v_max_i32_e32 v14, v13, v5
	v_min_i32_e32 v5, v13, v5
	v_max_i32_e32 v13, v12, v4
	v_min_i32_e32 v4, v12, v4
	v_max_i32_e32 v12, v18, v16
	v_min_i32_e32 v16, v18, v16
	v_max_i32_e32 v18, v11, v15
	v_min_i32_e32 v11, v11, v15
	v_max_i32_e32 v15, v10, v14
	v_min_i32_e32 v10, v10, v14
	v_max_i32_e32 v14, v17, v13
	v_min_i32_e32 v13, v17, v13
	v_max_i32_e32 v17, v1, v7
	v_min_i32_e32 v1, v1, v7
	v_max_i32_e32 v7, v2, v6
	v_min_i32_e32 v2, v2, v6
	v_max_i32_e32 v6, v9, v5
	v_min_i32_e32 v5, v9, v5
	v_max_i32_e32 v9, v8, v4
	v_min_i32_e32 v4, v8, v4
	v_max_i32_e32 v8, v12, v15
	v_min_i32_e32 v12, v12, v15
	v_max_i32_e32 v15, v18, v14
	v_min_i32_e32 v14, v18, v14
	v_max_i32_e32 v18, v16, v10
	v_min_i32_e32 v10, v16, v10
	v_max_i32_e32 v16, v11, v13
	v_min_i32_e32 v11, v11, v13
	v_max_i32_e32 v13, v17, v6
	v_min_i32_e32 v6, v17, v6
	v_max_i32_e32 v17, v7, v9
	v_min_i32_e32 v7, v7, v9
	v_max_i32_e32 v9, v1, v5
	v_min_i32_e32 v5, v1, v5
	v_max_i32_e32 v19, v2, v4
	v_min_i32_e32 v2, v2, v4
	v_max_i32_e32 v1, v8, v15
	v_min_i32_e32 v92, v8, v15
	v_max_i32_e32 v91, v12, v14
	v_min_i32_e32 v90, v12, v14
	v_max_i32_e32 v96, v5, v2
	v_min_i32_e32 v100, v5, v2
	v_and_b32_e32 v2, 0x7f, v1
	v_lshlrev_b32_e32 v4, 8, v92
	s_movk_i32 s12, 0x7f00
	v_and_or_b32 v2, v4, s12, v2
	v_lshlrev_b32_e32 v4, 16, v91
	v_lshlrev_b32_e32 v5, 24, v90
	v_max_i32_e32 v89, v18, v16
	v_min_i32_e32 v67, v18, v16
	v_and_b32_e32 v4, 0x7f0000, v4
	v_and_b32_e32 v5, 0x7f000000, v5
	v_max_i32_e32 v66, v10, v11
	v_min_i32_e32 v101, v10, v11
	v_or3_b32 v4, v2, v4, v5
	v_and_b32_e32 v2, 0x7f, v89
	v_lshlrev_b32_e32 v5, 8, v67
	v_max_i32_e32 v94, v6, v7
	v_min_i32_e32 v98, v6, v7
	v_and_or_b32 v2, v5, s12, v2
	v_lshlrev_b32_e32 v5, 16, v66
	v_lshlrev_b32_e32 v6, 24, v101
	v_max_i32_e32 v93, v13, v17
	v_min_i32_e32 v97, v13, v17
	v_and_b32_e32 v5, 0x7f0000, v5
	v_and_b32_e32 v6, 0x7f000000, v6
	v_or3_b32 v5, v2, v5, v6
	v_and_b32_e32 v2, 0x7f, v93
	v_lshlrev_b32_e32 v6, 8, v97
	v_and_or_b32 v2, v6, s12, v2
	v_lshlrev_b32_e32 v6, 16, v94
	v_lshlrev_b32_e32 v7, 24, v98
	v_max_i32_e32 v95, v9, v19
	v_min_i32_e32 v99, v9, v19
	v_and_b32_e32 v6, 0x7f0000, v6
	v_and_b32_e32 v7, 0x7f000000, v7
	v_or3_b32 v6, v2, v6, v7
	v_and_b32_e32 v2, 0x7f, v95
	v_lshlrev_b32_e32 v7, 8, v99
	v_and_or_b32 v2, v7, s12, v2
	v_lshlrev_b32_e32 v7, 16, v96
	v_lshlrev_b32_e32 v8, 24, v100
	v_and_b32_e32 v7, 0x7f0000, v7
	v_and_b32_e32 v8, 0x7f000000, v8
	v_or3_b32 v7, v2, v7, v8
	ds_write_b128 v69, v[4:7]
	global_load_dwordx4 v[20:23], v[64:65], off offset:256
	global_load_dwordx4 v[24:27], v[64:65], off offset:288
	global_load_dwordx4 v[28:31], v[64:65], off offset:320
	global_load_dwordx4 v[32:35], v[64:65], off offset:352
	global_load_dwordx4 v[36:39], v[64:65], off offset:384
	global_load_dwordx4 v[40:43], v[64:65], off offset:416
	global_load_dwordx4 v[44:47], v[64:65], off offset:448
	global_load_dwordx4 v[48:51], v[64:65], off offset:480
	v_bfrev_b32_e32 v2, 1
	s_mov_b32 s12, 0
	v_mov_b64_e32 v[64:65], v[60:61]
	v_bfrev_b32_e32 v102, 1
	v_bfrev_b32_e32 v103, 1
	v_bfrev_b32_e32 v104, 1
	v_bfrev_b32_e32 v105, 1
	v_bfrev_b32_e32 v106, 1
	v_bfrev_b32_e32 v107, 1
	v_bfrev_b32_e32 v108, 1
	v_bfrev_b32_e32 v109, 1
	v_bfrev_b32_e32 v110, 1
	v_bfrev_b32_e32 v111, 1
	v_bfrev_b32_e32 v112, 1
	v_bfrev_b32_e32 v113, 1
	v_bfrev_b32_e32 v114, 1
	v_bfrev_b32_e32 v115, 1
	v_bfrev_b32_e32 v116, 1
	global_load_dwordx4 v[128:131], v[64:65], off offset:-128
	global_load_dwordx4 v[132:135], v[64:65], off offset:-96
	global_load_dwordx4 v[136:139], v[64:65], off offset:-64
	global_load_dwordx4 v[140:143], v[64:65], off offset:-32
	global_load_dwordx4 v[144:147], v[64:65], off
	global_load_dwordx4 v[148:151], v[64:65], off offset:32
	global_load_dwordx4 v[152:155], v[64:65], off offset:64
	global_load_dwordx4 v[156:159], v[64:65], off offset:96

; #define GAS __attribute__((address_space(1)))
; template <int MASK> __device__ __forceinline__ int f2key(float f, int payload) { int b = __float_as_int(f); b ^= (b >> 31) & 0x7fffffff; return (b & ~MASK) | payload; }
; __device__ __forceinline__ void route_mfma(const bf16_t* __restrict__ PQb, const bf16_t* __restrict__ SKb, int* __restrict__ IDX, float* __restrict__ G) {
;     ...
; #pragma unroll 1
;             for (int blk = 0; blk < 4; ++blk) {
;                 f32x16 acc;
; #pragma unroll
;                 for (int r = 0; r < 16; ++r) acc[r] = 0.f;
; #pragma unroll
;                 for (int s = 0; s < 8; ++s)
;                     acc = __builtin_amdgcn_mfma_f32_32x32x16_bf16(*(const GAS bf16x8*)(kp + (size_t)blk * 32 * 128 + 16 * s), qf[s], acc, 0, 0, 0);
;                 int nk[16];
;                 const int pay = (32 * blk) | (hi << 2);
; #pragma unroll
;                 for (int r = 0; r < 16; ++r) nk[r] = f2key<0x7f>(acc[r], pay | ((r & 3) + 8 * (r >> 2)));
;                 bitonic_sort16<false>(nk);
; #pragma unroll
;                 for (int i = 0; i < 16; ++i) t0[i] = imax(t0[i], nk[i]);
;                 bitonic_merge16<true>(t0);
;             }
.Lrt_skip_4:
	v_add_u32_e32 v118, s12, v70
	s_add_i32 s12, s12, 32
	s_cmpk_lg_i32 s12, 0x80
	s_nop 8
	v_ashrrev_i32_e32 v117, 31, v4
	v_and_b32_e32 v117, 0x7fffff80, v117
	v_and_b32_e32 v4, 0xffffff80, v4
	v_xad_u32 v4, v117, v4, v118
	v_ashrrev_i32_e32 v117, 31, v5
	v_and_b32_e32 v5, 0xffffff80, v5
	v_bitop3_b32 v5, v117, v5, s3 bitop3:0x6c
	v_ashrrev_i32_e32 v117, 31, v6
	v_and_b32_e32 v6, 0xffffff80, v6
	v_bitop3_b32 v6, v117, v6, s3 bitop3:0x6c
	v_ashrrev_i32_e32 v117, 31, v7
	v_and_b32_e32 v7, 0xffffff80, v7
	v_bitop3_b32 v7, v117, v7, s3 bitop3:0x6c
	v_ashrrev_i32_e32 v117, 31, v8
	v_and_b32_e32 v8, 0xffffff80, v8
	v_bitop3_b32 v8, v117, v8, s3 bitop3:0x6c
	v_ashrrev_i32_e32 v117, 31, v9
	v_and_b32_e32 v9, 0xffffff80, v9
	v_bitop3_b32 v9, v117, v9, s3 bitop3:0x6c
	v_ashrrev_i32_e32 v117, 31, v10
	v_and_b32_e32 v10, 0xffffff80, v10
	v_bitop3_b32 v10, v117, v10, s3 bitop3:0x6c
	v_ashrrev_i32_e32 v117, 31, v11
	v_and_b32_e32 v11, 0xffffff80, v11
	v_bitop3_b32 v11, v117, v11, s3 bitop3:0x6c
	v_ashrrev_i32_e32 v117, 31, v12
	v_and_b32_e32 v12, 0xffffff80, v12
	v_bitop3_b32 v12, v117, v12, s3 bitop3:0x6c
	v_ashrrev_i32_e32 v117, 31, v13
	v_and_b32_e32 v13, 0xffffff80, v13
	v_bitop3_b32 v13, v117, v13, s3 bitop3:0x6c
	v_ashrrev_i32_e32 v117, 31, v14
	v_and_b32_e32 v14, 0xffffff80, v14
	v_bitop3_b32 v14, v117, v14, s3 bitop3:0x6c
	v_ashrrev_i32_e32 v117, 31, v15
	v_and_b32_e32 v15, 0xffffff80, v15
	v_bitop3_b32 v15, v117, v15, s3 bitop3:0x6c
	v_ashrrev_i32_e32 v117, 31, v16
	v_and_b32_e32 v16, 0xffffff80, v16
	v_bitop3_b32 v16, v117, v16, s3 bitop3:0x6c
	v_ashrrev_i32_e32 v117, 31, v17
	v_and_b32_e32 v17, 0xffffff80, v17
	v_bitop3_b32 v17, v117, v17, s3 bitop3:0x6c
	v_ashrrev_i32_e32 v117, 31, v18
	v_and_b32_e32 v18, 0xffffff80, v18
	v_bitop3_b32 v18, v117, v18, s3 bitop3:0x6c
	v_ashrrev_i32_e32 v117, 31, v19
	v_and_b32_e32 v19, 0xffffff80, v19
	v_bitop3_b32 v19, v117, v19, s3 bitop3:0x6c
	v_add3_u32 v5, v118, v5, 1
	v_add3_u32 v6, v118, v6, 2
	v_add3_u32 v7, v118, v7, 3
	v_add3_u32 v8, v118, v8, 8
	v_add3_u32 v9, v118, v9, 9
	v_add3_u32 v10, v118, v10, 10
	v_add3_u32 v11, v118, v11, 11
	v_add3_u32 v12, v118, v12, 16
	v_add3_u32 v13, v118, v13, 17
	v_add3_u32 v14, v118, v14, 18
	v_add3_u32 v15, v118, v15, 19
	v_add3_u32 v16, v118, v16, 24
	v_add3_u32 v17, v118, v17, 25
	v_add3_u32 v18, v118, v18, 26
	v_add3_u32 v19, v118, v19, 27
	v_max_i32_e32 v117, v4, v5
	v_min_i32_e32 v4, v4, v5
	v_max_i32_e32 v5, v6, v7
	v_min_i32_e32 v6, v6, v7
	v_max_i32_e32 v7, v8, v9
	v_min_i32_e32 v8, v8, v9
	v_max_i32_e32 v9, v10, v11
	v_min_i32_e32 v10, v10, v11
	v_max_i32_e32 v11, v12, v13
	v_min_i32_e32 v12, v12, v13
	v_max_i32_e32 v13, v14, v15
	v_min_i32_e32 v14, v14, v15
	v_max_i32_e32 v15, v16, v17
	v_min_i32_e32 v16, v16, v17
	v_max_i32_e32 v17, v18, v19
	v_min_i32_e32 v18, v18, v19
	v_max_i32_e32 v19, v4, v5
	v_min_i32_e32 v4, v4, v5
	v_max_i32_e32 v5, v117, v6
	v_min_i32_e32 v6, v117, v6
	v_max_i32_e32 v117, v8, v9
	v_min_i32_e32 v8, v8, v9
	v_max_i32_e32 v9, v7, v10
	v_min_i32_e32 v7, v7, v10
	v_max_i32_e32 v10, v12, v13
	v_min_i32_e32 v12, v12, v13
	v_max_i32_e32 v13, v11, v14
	v_min_i32_e32 v11, v11, v14
	v_max_i32_e32 v14, v16, v17
	v_min_i32_e32 v16, v16, v17
	v_max_i32_e32 v17, v15, v18
	v_min_i32_e32 v15, v15, v18
	v_max_i32_e32 v18, v4, v6
	v_min_i32_e32 v4, v4, v6
	v_max_i32_e32 v6, v19, v5
	v_min_i32_e32 v5, v19, v5
	v_max_i32_e32 v19, v117, v9
	v_min_i32_e32 v9, v117, v9
	v_max_i32_e32 v117, v8, v7
	v_min_i32_e32 v7, v8, v7
	v_max_i32_e32 v8, v12, v11
	v_min_i32_e32 v11, v12, v11
	v_max_i32_e32 v12, v10, v13
	v_min_i32_e32 v10, v10, v13
	v_max_i32_e32 v13, v14, v17
	v_min_i32_e32 v14, v14, v17
	v_max_i32_e32 v17, v16, v15
	v_min_i32_e32 v15, v16, v15
	v_max_i32_e32 v16, v4, v19
	v_min_i32_e32 v4, v4, v19
	v_max_i32_e32 v19, v18, v9
	v_min_i32_e32 v9, v18, v9
	v_max_i32_e32 v18, v5, v117
	v_min_i32_e32 v5, v5, v117
	v_max_i32_e32 v117, v6, v7
	v_min_i32_e32 v6, v6, v7
	v_max_i32_e32 v7, v11, v13
	v_min_i32_e32 v11, v11, v13
	v_max_i32_e32 v13, v8, v14
	v_min_i32_e32 v8, v8, v14
	v_max_i32_e32 v14, v10, v17
	v_min_i32_e32 v10, v10, v17
	v_max_i32_e32 v17, v12, v15
	v_min_i32_e32 v12, v12, v15
	v_max_i32_e32 v15, v4, v5
	v_min_i32_e32 v4, v4, v5
	v_max_i32_e32 v5, v9, v6
	v_min_i32_e32 v6, v9, v6
	v_max_i32_e32 v9, v16, v18
	v_min_i32_e32 v16, v16, v18
	v_max_i32_e32 v18, v19, v117
	v_min_i32_e32 v19, v19, v117
	v_max_i32_e32 v117, v7, v14
	v_min_i32_e32 v7, v7, v14
	v_max_i32_e32 v14, v13, v17
	v_min_i32_e32 v13, v13, v17
	v_max_i32_e32 v17, v11, v10
	v_min_i32_e32 v10, v11, v10
	v_max_i32_e32 v11, v8, v12
	v_min_i32_e32 v8, v8, v12
	v_max_i32_e32 v12, v4, v6
	v_min_i32_e32 v4, v4, v6
	v_max_i32_e32 v6, v15, v5
	v_min_i32_e32 v5, v15, v5
	v_max_i32_e32 v15, v16, v19
	v_min_i32_e32 v16, v16, v19
	v_max_i32_e32 v19, v9, v18
	v_min_i32_e32 v9, v9, v18
	v_max_i32_e32 v18, v117, v14
	v_min_i32_e32 v14, v117, v14
	v_max_i32_e32 v117, v7, v13
	v_min_i32_e32 v7, v7, v13
	v_max_i32_e32 v13, v17, v11
	v_min_i32_e32 v11, v17, v11
	v_max_i32_e32 v17, v10, v8
	v_min_i32_e32 v8, v10, v8
	v_max_i32_e32 v10, v4, v18
	v_min_i32_e32 v4, v4, v18
	v_max_i32_e32 v18, v12, v14
	v_min_i32_e32 v12, v12, v14
	v_max_i32_e32 v14, v5, v117
	v_min_i32_e32 v5, v5, v117
	v_max_i32_e32 v117, v6, v7
	v_min_i32_e32 v6, v6, v7
	v_max_i32_e32 v7, v16, v13
	v_min_i32_e32 v13, v16, v13
	v_max_i32_e32 v16, v15, v11
	v_min_i32_e32 v11, v15, v11
	v_max_i32_e32 v15, v9, v17
	v_min_i32_e32 v9, v9, v17
	v_max_i32_e32 v17, v19, v8
	v_min_i32_e32 v8, v19, v8
	v_max_i32_e32 v19, v4, v13
	v_min_i32_e32 v4, v4, v13
	v_max_i32_e32 v13, v12, v11
	v_min_i32_e32 v11, v12, v11
	v_max_i32_e32 v12, v5, v9
; template <bool DESC> __device__ __forceinline__ void bitonic_sort16(int (&k)[16]) {
; #pragma unroll
;     for (int size = 2; size <= 16; size <<= 1)
; #pragma unroll
;         for (int stride = size >> 1; stride > 0; stride >>= 1)
; #pragma unroll
;             for (int i = 0; i < 16; ++i) {
;                 const int j = i ^ stride;
;                 if (j > i) { const bool dd = (((i & size) == 0) == DESC);
;                              const int a = k[i], b = k[j], mx = imax(a, b), mn = imin(a, b); k[i] = dd ? mx : mn; k[j] = dd ? mn : mx; }
;             }
; }
; template <bool DESC> __device__ __forceinline__ void bitonic_merge16(int (&k)[16]) {
; #pragma unroll
;     for (int stride = 8; stride > 0; stride >>= 1)
; #pragma unroll
;         for (int i = 0; i < 16; ++i) {
;             const int j = i ^ stride;
;             if (j > i) { const int a = k[i], b = k[j], mx = imax(a, b), mn = imin(a, b); k[i] = DESC ? mx : mn; k[j] = DESC ? mn : mx; }
;         }
; }
; __device__ __forceinline__ void partner_merge16(int (&k)[16], int hi) {
;     int pr[16];
; #pragma unroll
;     for (int i = 0; i < 16; ++i) { auto rr = __builtin_amdgcn_permlane32_swap((unsigned)k[i], (unsigned)k[i], false, false); pr[i] = hi ? (int)rr[0] : (int)rr[1]; }
; #pragma unroll
;     for (int i = 0; i < 16; ++i) k[i] = imax(k[i], pr[15 - i]);
;     bitonic_merge16<true>(k);
	v_min_i32_e32 v5, v5, v9
	v_max_i32_e32 v9, v6, v8
	v_min_i32_e32 v6, v6, v8
	v_max_i32_e32 v8, v10, v7
	v_min_i32_e32 v7, v10, v7
	v_max_i32_e32 v10, v18, v16
	v_min_i32_e32 v16, v18, v16
	v_max_i32_e32 v18, v14, v15
	v_min_i32_e32 v14, v14, v15
	v_max_i32_e32 v15, v117, v17
	v_min_i32_e32 v17, v117, v17
	v_max_i32_e32 v117, v4, v5
	v_min_i32_e32 v4, v4, v5
	v_max_i32_e32 v5, v11, v6
	v_min_i32_e32 v6, v11, v6
	v_max_i32_e32 v11, v19, v12
	v_min_i32_e32 v12, v19, v12
	v_max_i32_e32 v19, v13, v9
	v_min_i32_e32 v9, v13, v9
	v_max_i32_e32 v13, v7, v14
	v_min_i32_e32 v7, v7, v14
	v_max_i32_e32 v14, v16, v17
	v_min_i32_e32 v16, v16, v17
	v_max_i32_e32 v17, v8, v18
	v_min_i32_e32 v8, v8, v18
	v_max_i32_e32 v18, v10, v15
	v_min_i32_e32 v10, v10, v15
	v_min_i32_e32 v15, v4, v6
	v_min_i32_e32 v118, v117, v5
	v_min_i32_e32 v119, v12, v9
	v_min_i32_e32 v120, v11, v19
	v_min_i32_e32 v121, v7, v16
	v_min_i32_e32 v122, v13, v14
	v_min_i32_e32 v123, v8, v10
	v_min_i32_e32 v124, v17, v18
	v_max_i32_e32 v2, v2, v15
	v_max3_i32 v4, v102, v4, v6
	v_max_i32_e32 v6, v103, v118
	v_max3_i32 v5, v104, v117, v5
	v_max_i32_e32 v15, v105, v119
	v_max3_i32 v9, v106, v12, v9
	v_max_i32_e32 v12, v107, v120
	v_max3_i32 v11, v108, v11, v19
	v_max_i32_e32 v19, v109, v121
	v_max3_i32 v7, v110, v7, v16
	v_max_i32_e32 v16, v111, v122
	v_max3_i32 v13, v112, v13, v14
	v_max_i32_e32 v14, v113, v123
	v_max3_i32 v8, v114, v8, v10
	v_max_i32_e32 v10, v115, v124
	v_max3_i32 v17, v116, v17, v18
	v_max_i32_e32 v18, v2, v19
	v_min_i32_e32 v2, v2, v19
	v_max_i32_e32 v19, v4, v7
	v_min_i32_e32 v4, v4, v7
	v_max_i32_e32 v7, v6, v16
	v_min_i32_e32 v6, v6, v16
	v_max_i32_e32 v16, v5, v13
	v_min_i32_e32 v5, v5, v13
	v_max_i32_e32 v13, v15, v14
	v_min_i32_e32 v14, v15, v14
	v_max_i32_e32 v15, v9, v8
	v_min_i32_e32 v8, v9, v8
	v_max_i32_e32 v9, v12, v10
	v_min_i32_e32 v10, v12, v10
	v_max_i32_e32 v12, v11, v17
	v_min_i32_e32 v11, v11, v17
	v_max_i32_e32 v17, v18, v13
	v_min_i32_e32 v13, v18, v13
	v_max_i32_e32 v18, v19, v15
	v_min_i32_e32 v15, v19, v15
	v_max_i32_e32 v19, v7, v9
	v_min_i32_e32 v7, v7, v9
	v_max_i32_e32 v9, v16, v12
	v_min_i32_e32 v12, v16, v12
	v_max_i32_e32 v16, v2, v14
	v_min_i32_e32 v2, v2, v14
	v_max_i32_e32 v14, v4, v8
	v_min_i32_e32 v4, v4, v8
	v_max_i32_e32 v8, v6, v10
	v_min_i32_e32 v6, v6, v10
	v_max_i32_e32 v10, v5, v11
	v_min_i32_e32 v5, v5, v11
	v_max_i32_e32 v11, v17, v19
	v_min_i32_e32 v17, v17, v19
	v_max_i32_e32 v19, v18, v9
	v_min_i32_e32 v9, v18, v9
	v_max_i32_e32 v18, v13, v7
	v_min_i32_e32 v7, v13, v7
	v_max_i32_e32 v13, v15, v12
	v_min_i32_e32 v12, v15, v12
	v_max_i32_e32 v15, v16, v8
	v_min_i32_e32 v8, v16, v8
	v_max_i32_e32 v16, v14, v10
	v_min_i32_e32 v10, v14, v10
	v_max_i32_e32 v14, v2, v6
	v_min_i32_e32 v6, v2, v6
	v_max_i32_e32 v114, v4, v5
	v_min_i32_e32 v4, v4, v5
	v_max_i32_e32 v2, v11, v19
	v_min_i32_e32 v102, v11, v19
	v_max_i32_e32 v103, v17, v9
	v_min_i32_e32 v104, v17, v9
	v_max_i32_e32 v105, v18, v13
	v_min_i32_e32 v106, v18, v13
	v_max_i32_e32 v107, v7, v12
	v_min_i32_e32 v108, v7, v12
	v_max_i32_e32 v109, v15, v16
	v_min_i32_e32 v110, v15, v16
	v_max_i32_e32 v111, v8, v10
	v_min_i32_e32 v112, v8, v10
	v_max_i32_e32 v113, v14, v114
	v_min_i32_e32 v114, v14, v114
	v_max_i32_e32 v115, v6, v4
	v_min_i32_e32 v116, v6, v4
	s_cbranch_scc1 .LBB0_1212
	v_mov_b32_e32 v4, v2
	v_mov_b32_e32 v5, v2
	s_nop 1
	v_permlane32_swap_b32_e32 v4, v5
	v_cndmask_b32_e64 v4, v4, v5, s[40:41]
	v_mov_b32_e32 v5, v102
	v_mov_b32_e32 v6, v102
	s_nop 1
	v_permlane32_swap_b32_e32 v5, v6
	v_cndmask_b32_e64 v5, v5, v6, s[40:41]
	v_mov_b32_e32 v6, v103
	v_mov_b32_e32 v7, v103
	s_nop 1
	v_permlane32_swap_b32_e32 v6, v7
	v_cndmask_b32_e64 v6, v6, v7, s[40:41]
	v_mov_b32_e32 v7, v104
	v_mov_b32_e32 v8, v104
	s_nop 1
	v_permlane32_swap_b32_e32 v7, v8
	v_cndmask_b32_e64 v7, v7, v8, s[40:41]
	v_mov_b32_e32 v8, v105
	v_mov_b32_e32 v9, v105
	s_nop 1
	v_permlane32_swap_b32_e32 v8, v9
	v_cndmask_b32_e64 v8, v8, v9, s[40:41]
	v_mov_b32_e32 v9, v106
	v_mov_b32_e32 v10, v106
	s_nop 1
	v_permlane32_swap_b32_e32 v9, v10
	v_cndmask_b32_e64 v9, v9, v10, s[40:41]
	v_mov_b32_e32 v10, v107
	v_mov_b32_e32 v11, v107
	s_nop 1
	v_permlane32_swap_b32_e32 v10, v11
	v_cndmask_b32_e64 v10, v10, v11, s[40:41]
	v_mov_b32_e32 v11, v108
	v_mov_b32_e32 v12, v108
	s_nop 1
	v_permlane32_swap_b32_e32 v11, v12
	v_cndmask_b32_e64 v11, v11, v12, s[40:41]
	v_mov_b32_e32 v12, v109
	v_mov_b32_e32 v13, v109
	s_nop 1
	v_permlane32_swap_b32_e32 v12, v13
	v_cndmask_b32_e64 v12, v12, v13, s[40:41]
	v_mov_b32_e32 v13, v110
	v_mov_b32_e32 v14, v110
	s_nop 1
	v_permlane32_swap_b32_e32 v13, v14
	v_cndmask_b32_e64 v13, v13, v14, s[40:41]
	v_mov_b32_e32 v14, v111
	v_mov_b32_e32 v15, v111
	s_nop 1
	v_permlane32_swap_b32_e32 v14, v15
	v_cndmask_b32_e64 v14, v14, v15, s[40:41]
	v_mov_b32_e32 v15, v112
	v_mov_b32_e32 v16, v112
	s_nop 1
	v_permlane32_swap_b32_e32 v15, v16
	v_cndmask_b32_e64 v15, v15, v16, s[40:41]
	v_mov_b32_e32 v16, v113
	v_mov_b32_e32 v17, v113
	s_nop 1
	v_permlane32_swap_b32_e32 v16, v17
	v_cndmask_b32_e64 v16, v16, v17, s[40:41]
	v_mov_b32_e32 v17, v114
	v_mov_b32_e32 v18, v114
	s_nop 1
	v_permlane32_swap_b32_e32 v17, v18
	v_cndmask_b32_e64 v17, v17, v18, s[40:41]
	v_mov_b32_e32 v18, v115
	v_mov_b32_e32 v19, v115
	s_nop 1
	v_permlane32_swap_b32_e32 v18, v19
	v_cndmask_b32_e64 v18, v18, v19, s[40:41]
	v_mov_b32_e32 v19, v116
	v_mov_b32_e32 v20, v116
	s_nop 1
	v_permlane32_swap_b32_e32 v19, v20
	v_cndmask_b32_e64 v19, v19, v20, s[40:41]
; template <int MASK> __device__ __forceinline__ int f2key(float f, int payload) { int b = __float_as_int(f); b ^= (b >> 31) & 0x7fffffff; return (b & ~MASK) | payload; }
; template <int MASK> __device__ __forceinline__ float key2f(int k) { int b = k & ~MASK; b ^= (b >> 31) & 0x7fffffff; return __int_as_float(b); }
; __device__ __forceinline__ void partner_merge16(int (&k)[16], int hi) {
;     int pr[16];
; #pragma unroll
;     for (int i = 0; i < 16; ++i) { auto rr = __builtin_amdgcn_permlane32_swap((unsigned)k[i], (unsigned)k[i], false, false); pr[i] = hi ? (int)rr[0] : (int)rr[1]; }
; #pragma unroll
;     for (int i = 0; i < 16; ++i) k[i] = imax(k[i], pr[15 - i]);
;     bitonic_merge16<true>(k);
; __device__ __forceinline__ void route_mfma(const bf16_t* __restrict__ PQb, const bf16_t* __restrict__ SKb, int* __restrict__ IDX, float* __restrict__ G) {
;     ...
;             partner_merge16(t0, hi);
; #pragma unroll
;             for (int i = 0; i < 16; ++i) sv[p][i] = t0[i];
; #pragma unroll
;             for (int q4 = 0; q4 < 4; ++q4)
;                 *(unsigned*)(myslot + p * 16 + q4 * 4) = (unsigned)(t0[4 * q4] & 0x7f) | ((unsigned)(t0[4 * q4 + 1] & 0x7f) << 8) | ((unsigned)(t0[4 * q4 + 2] & 0x7f) << 16) | ((unsigned)(t0[4 * q4 + 3] & 0x7f) << 24);
;         }
;         float f0[16], f1[16];
; #pragma unroll
;         for (int i = 0; i < 16; ++i) { f0[i] = key2f<0x7f>(sv[0][i]); f1[i] = key2f<0x7f>(sv[1][i]); }
;         int cd[32];
;         {
;             constexpr int PA[50] = {0,0,0,0,0,0,0,0,0,0,0,0,0,0,0,0, 1,1,1,1,1,1,1,1, 2,2,2,2,2, 3,3,3,3, 4,4,4, 5,5, 6,6, 7,7, 8,9,10,11,12,13,14,15};
;             constexpr int PB[50] = {0,1,2,3,4,5,6,7,8,9,10,11,12,13,14,15, 0,1,2,3,4,5,6,7, 0,1,2,3,4, 0,1,2,3, 0,1,2, 0,1, 0,1, 0,1, 0,0,0,0,0,0,0,0};
; #pragma unroll
;             for (int q = 0; q < 25; ++q) {
;                 const int a0 = PA[2 * q], b0 = PB[2 * q], a1 = PA[2 * q + 1], b1 = PB[2 * q + 1];
;                 const float s0 = f0[a0] + f1[b0], s1 = f0[a1] + f1[b1];
;                 cd[q] = hi ? f2key<0xff>(s1, a1 * 16 + b1) : f2key<0xff>(s0, a0 * 16 + b0);
	v_max_i32_e32 v2, v2, v19
	v_max_i32_e32 v18, v102, v18
	v_max_i32_e32 v17, v103, v17
	v_max_i32_e32 v16, v104, v16
	v_max_i32_e32 v15, v105, v15
	v_max_i32_e32 v14, v106, v14
	v_max_i32_e32 v13, v107, v13
	v_max_i32_e32 v12, v108, v12
	v_max_i32_e32 v11, v109, v11
	v_max_i32_e32 v10, v110, v10
	v_max_i32_e32 v9, v111, v9
	v_max_i32_e32 v8, v112, v8
	v_max_i32_e32 v7, v113, v7
	v_max_i32_e32 v6, v114, v6
	v_max_i32_e32 v5, v115, v5
	v_max_i32_e32 v4, v116, v4
	v_max_i32_e32 v19, v2, v11
	v_min_i32_e32 v2, v2, v11
	v_max_i32_e32 v11, v18, v10
	v_min_i32_e32 v10, v18, v10
	v_max_i32_e32 v18, v17, v9
	v_min_i32_e32 v9, v17, v9
	v_max_i32_e32 v17, v16, v8
	v_min_i32_e32 v8, v16, v8
	v_max_i32_e32 v16, v15, v7
	v_min_i32_e32 v7, v15, v7
	v_max_i32_e32 v15, v14, v6
	v_min_i32_e32 v6, v14, v6
	v_max_i32_e32 v14, v13, v5
	v_min_i32_e32 v5, v13, v5
	v_max_i32_e32 v13, v12, v4
	v_min_i32_e32 v4, v12, v4
	v_max_i32_e32 v12, v19, v16
	v_min_i32_e32 v16, v19, v16
	v_max_i32_e32 v19, v11, v15
	v_min_i32_e32 v11, v11, v15
	v_max_i32_e32 v15, v18, v14
	v_min_i32_e32 v14, v18, v14
	v_max_i32_e32 v18, v17, v13
	v_min_i32_e32 v13, v17, v13
	v_max_i32_e32 v17, v2, v7
	v_min_i32_e32 v2, v2, v7
	v_max_i32_e32 v7, v10, v6
	v_min_i32_e32 v6, v10, v6
	v_max_i32_e32 v10, v9, v5
	v_min_i32_e32 v5, v9, v5
	v_max_i32_e32 v9, v8, v4
	v_min_i32_e32 v4, v8, v4
	v_max_i32_e32 v8, v12, v15
	v_min_i32_e32 v21, v12, v15
	v_max_i32_e32 v15, v16, v14
	v_min_i32_e32 v14, v16, v14
	v_max_i32_e32 v16, v11, v13
	v_max_i32_e32 v31, v19, v18
	v_min_i32_e32 v18, v19, v18
	v_min_i32_e32 v11, v11, v13
	v_max_i32_e32 v19, v7, v9
	v_min_i32_e32 v7, v7, v9
	v_max_i32_e32 v9, v2, v5
	v_min_i32_e32 v2, v2, v5
	v_max_i32_e32 v5, v6, v4
	v_max_i32_e32 v12, v15, v16
	v_min_i32_e32 v23, v15, v16
	v_max_i32_e32 v13, v17, v10
	v_min_i32_e32 v17, v17, v10
	v_min_i32_e32 v4, v6, v4
	v_max_i32_e32 v28, v14, v11
	v_min_i32_e32 v10, v14, v11
	v_max_i32_e32 v29, v9, v5
	v_min_i32_e32 v24, v9, v5
	v_and_b32_e32 v5, 0x7f, v12
	v_lshlrev_b32_e32 v6, 8, v23
	s_movk_i32 s12, 0x7f00
	v_max_i32_e32 v27, v17, v7
	v_min_i32_e32 v22, v17, v7
	v_and_or_b32 v5, v6, s12, v5
	v_lshlrev_b32_e32 v6, 16, v28
	v_lshlrev_b32_e32 v7, 24, v10
	v_max_i32_e32 v26, v13, v19
	v_min_i32_e32 v20, v13, v19
	v_and_b32_e32 v6, 0x7f0000, v6
	v_and_b32_e32 v7, 0x7f000000, v7
	v_or3_b32 v15, v5, v6, v7
	v_and_b32_e32 v5, 0x7f, v26
	v_lshlrev_b32_e32 v6, 8, v20
	v_and_or_b32 v5, v6, s12, v5
	v_lshlrev_b32_e32 v6, 16, v27
	v_lshlrev_b32_e32 v7, 24, v22
	v_and_b32_e32 v6, 0x7f0000, v6
	v_and_b32_e32 v7, 0x7f000000, v7
	v_max_i32_e32 v30, v2, v4
	v_min_i32_e32 v25, v2, v4
	v_or3_b32 v16, v5, v6, v7
	v_and_b32_e32 v5, 0x7f, v29
	v_lshlrev_b32_e32 v6, 8, v24
	v_and_or_b32 v5, v6, s12, v5
	v_lshlrev_b32_e32 v6, 16, v30
	v_lshlrev_b32_e32 v7, 24, v25
	v_and_b32_e32 v6, 0x7f0000, v6
	v_and_b32_e32 v7, 0x7f000000, v7
	v_max_i32_e32 v33, v21, v18
	v_or3_b32 v17, v5, v6, v7
	v_and_b32_e32 v5, 0xffffff80, v1
	v_ashrrev_i32_e32 v1, 31, v1
	s_brev_b32 s15, -2
	v_bitop3_b32 v6, v1, v5, s15 bitop3:0x6c
	v_and_b32_e32 v1, 0xffffff80, v33
	v_ashrrev_i32_e32 v5, 31, v33
	v_max_i32_e32 v32, v8, v31
	v_bitop3_b32 v9, v5, v1, s15 bitop3:0x6c
	v_min_i32_e32 v1, v8, v31
	v_and_b32_e32 v2, 0x7f, v32
	v_min_i32_e32 v5, v21, v18
	v_lshlrev_b32_e32 v7, 8, v1
	v_lshlrev_b32_e32 v4, 16, v33
	v_and_or_b32 v2, v7, s12, v2
	v_lshlrev_b32_e32 v7, 24, v5
	v_and_b32_e32 v4, 0x7f0000, v4
	v_and_b32_e32 v7, 0x7f000000, v7
	v_or3_b32 v14, v2, v4, v7
	v_and_b32_e32 v2, 0xffffff80, v1
	v_and_b32_e32 v4, 0xffffff80, v5
	v_ashrrev_i32_e32 v1, 31, v1
	v_ashrrev_i32_e32 v5, 31, v5
	v_and_b32_e32 v1, 0x7fffffff, v1
	v_and_b32_e32 v5, 0x7fffffff, v5
	v_xor_b32_e32 v1, v1, v2
	v_xor_b32_e32 v2, v5, v4
	v_ashrrev_i32_e32 v5, 31, v32
	v_and_b32_e32 v8, 0x7fffffff, v5
	v_ashrrev_i32_e32 v5, 31, v101
	v_and_b32_e32 v4, 0xffffff80, v101
	v_and_b32_e32 v7, 0xffffff80, v32
	v_and_b32_e32 v5, 0x7fffffff, v5
	v_xor_b32_e32 v5, v5, v4
	v_xor_b32_e32 v4, v8, v7
	ds_write_b128 v69, v[14:17] offset:16
	s_and_saveexec_b64 s[12:13], s[42:43]
	s_xor_b64 s[12:13], exec, s[12:13]
	s_cbranch_execz .LBB0_1215
	v_ashrrev_i32_e32 v7, 31, v100
	v_and_b32_e32 v8, 0xffffff80, v100
	v_bitop3_b32 v7, v7, v8, s15 bitop3:0x6c
	v_ashrrev_i32_e32 v8, 31, v99
	v_and_b32_e32 v11, 0xffffff80, v99
	v_bitop3_b32 v14, v8, v11, s15 bitop3:0x6c
	v_ashrrev_i32_e32 v8, 31, v98
	v_and_b32_e32 v11, 0xffffff80, v98
	v_bitop3_b32 v15, v8, v11, s15 bitop3:0x6c
	v_ashrrev_i32_e32 v8, 31, v97
	v_and_b32_e32 v11, 0xffffff80, v97
	v_bitop3_b32 v8, v8, v11, s15 bitop3:0x6c
	v_ashrrev_i32_e32 v11, 31, v10
	v_and_b32_e32 v10, 0xffffff80, v10
	v_bitop3_b32 v10, v11, v10, s15 bitop3:0x6c
	v_ashrrev_i32_e32 v11, 31, v23
	v_and_b32_e32 v13, 0xffffff80, v23
	v_bitop3_b32 v11, v11, v13, s15 bitop3:0x6c
	v_ashrrev_i32_e32 v13, 31, v25
	v_and_b32_e32 v16, 0xffffff80, v25
	v_bitop3_b32 v17, v13, v16, s15 bitop3:0x6c
	v_ashrrev_i32_e32 v13, 31, v24
	v_and_b32_e32 v16, 0xffffff80, v24
	v_bitop3_b32 v18, v13, v16, s15 bitop3:0x6c
	v_ashrrev_i32_e32 v13, 31, v22
	v_and_b32_e32 v16, 0xffffff80, v22
	v_bitop3_b32 v19, v13, v16, s15 bitop3:0x6c
	v_ashrrev_i32_e32 v13, 31, v20
	v_and_b32_e32 v16, 0xffffff80, v20
	v_bitop3_b32 v21, v13, v16, s15 bitop3:0x6c
	v_add_f32_e32 v13, v1, v6
	v_ashrrev_i32_e32 v16, 31, v13
	v_and_b32_e32 v16, 0x7fffff00, v16
	v_and_b32_e32 v13, 0xffffff00, v13
	v_bitop3_b32 v16, v16, 1, v13 bitop3:0xde
	v_mov_b32_e32 v13, v1
	v_mov_b32_e32 v1, v9
